# diff attention softmax: max-update path moved out of line, per-lane partial row sums reduced once at the end, fully masked wave-tiles skipped
# speedup vs baseline: 1.0175x; 1.0049x over previous
.LBB0_790:
	s_sub_i32 s73, s56, 158
	s_cmp_gt_i32 s73, s4
	s_cbranch_scc1 .Ld16a_end0
	ds_read_b128 v[238:241], v218 offset:0
	ds_read_b128 v[242:245], v219 offset:0
	ds_read_b128 v[246:249], v218 offset:128
	s_waitcnt lgkmcnt(2)
	v_mfma_f32_16x16x32_bf16 v[130:133], v[238:241], v[162:165], 0
	v_mfma_f32_16x16x32_bf16 v[146:149], v[238:241], v[178:181], 0
	ds_read_b128 v[238:241], v219 offset:128
	s_waitcnt lgkmcnt(2)
	v_mfma_f32_16x16x32_bf16 v[130:133], v[242:245], v[166:169], v[130:133]
	v_mfma_f32_16x16x32_bf16 v[146:149], v[242:245], v[182:185], v[146:149]
	ds_read_b128 v[242:245], v218 offset:4096
	s_waitcnt lgkmcnt(2)
	v_mfma_f32_16x16x32_bf16 v[130:133], v[246:249], v[170:173], v[130:133]
	v_mfma_f32_16x16x32_bf16 v[146:149], v[246:249], v[186:189], v[146:149]
	ds_read_b128 v[246:249], v219 offset:4096
	s_waitcnt lgkmcnt(2)
	v_mfma_f32_16x16x32_bf16 v[130:133], v[238:241], v[174:177], v[130:133]
	v_mfma_f32_16x16x32_bf16 v[146:149], v[238:241], v[190:193], v[146:149]
	ds_read_b128 v[238:241], v218 offset:4224
	s_waitcnt lgkmcnt(2)
	v_mfma_f32_16x16x32_bf16 v[134:137], v[242:245], v[162:165], 0
	v_mfma_f32_16x16x32_bf16 v[150:153], v[242:245], v[178:181], 0
	ds_read_b128 v[242:245], v219 offset:4224
	s_waitcnt lgkmcnt(2)
	v_mfma_f32_16x16x32_bf16 v[134:137], v[246:249], v[166:169], v[134:137]
	v_mfma_f32_16x16x32_bf16 v[150:153], v[246:249], v[182:185], v[150:153]
	ds_read_b128 v[246:249], v218 offset:8192
	s_waitcnt lgkmcnt(2)
	v_mfma_f32_16x16x32_bf16 v[134:137], v[238:241], v[170:173], v[134:137]
	v_mfma_f32_16x16x32_bf16 v[150:153], v[238:241], v[186:189], v[150:153]
	ds_read_b128 v[238:241], v219 offset:8192
	s_waitcnt lgkmcnt(2)
	v_mfma_f32_16x16x32_bf16 v[134:137], v[242:245], v[174:177], v[134:137]
	v_mfma_f32_16x16x32_bf16 v[150:153], v[242:245], v[190:193], v[150:153]
	ds_read_b128 v[242:245], v218 offset:8320
	s_waitcnt lgkmcnt(2)
	v_mfma_f32_16x16x32_bf16 v[138:141], v[246:249], v[162:165], 0
	v_mfma_f32_16x16x32_bf16 v[154:157], v[246:249], v[178:181], 0
	ds_read_b128 v[246:249], v219 offset:8320
	s_waitcnt lgkmcnt(2)
	v_mfma_f32_16x16x32_bf16 v[138:141], v[238:241], v[166:169], v[138:141]
	v_mfma_f32_16x16x32_bf16 v[154:157], v[238:241], v[182:185], v[154:157]
	ds_read_b128 v[238:241], v218 offset:12288
	s_waitcnt lgkmcnt(2)
	v_mfma_f32_16x16x32_bf16 v[138:141], v[242:245], v[170:173], v[138:141]
	v_mfma_f32_16x16x32_bf16 v[154:157], v[242:245], v[186:189], v[154:157]
	ds_read_b128 v[242:245], v219 offset:12288
	s_waitcnt lgkmcnt(2)
	v_mfma_f32_16x16x32_bf16 v[138:141], v[246:249], v[174:177], v[138:141]
	v_mfma_f32_16x16x32_bf16 v[154:157], v[246:249], v[190:193], v[154:157]
	ds_read_b128 v[246:249], v218 offset:12416
	s_waitcnt lgkmcnt(2)
	v_mfma_f32_16x16x32_bf16 v[142:145], v[238:241], v[162:165], 0
	v_mfma_f32_16x16x32_bf16 v[158:161], v[238:241], v[178:181], 0
	ds_read_b128 v[238:241], v219 offset:12416
	s_waitcnt lgkmcnt(2)
	v_mfma_f32_16x16x32_bf16 v[142:145], v[242:245], v[166:169], v[142:145]
	v_mfma_f32_16x16x32_bf16 v[158:161], v[242:245], v[182:185], v[158:161]
	s_waitcnt lgkmcnt(1)
	v_mfma_f32_16x16x32_bf16 v[142:145], v[246:249], v[170:173], v[142:145]
	v_mfma_f32_16x16x32_bf16 v[158:161], v[246:249], v[186:189], v[158:161]
	s_waitcnt lgkmcnt(0)
	v_mfma_f32_16x16x32_bf16 v[142:145], v[238:241], v[174:177], v[142:145]
	v_mfma_f32_16x16x32_bf16 v[158:161], v[238:241], v[190:193], v[158:161]
	s_nop 7
	s_nop 1
	s_sub_i32 s36, s56, 64
	s_cmp_le_i32 s36, s4
	s_cbranch_scc1 .Ld16a_nm0
	v_cmp_gt_i32_e64 s[74:75], 0, v233
	v_cmp_gt_i32_e64 s[76:77], 1, v233
	v_cmp_gt_i32_e64 s[78:79], 2, v233
	v_cmp_gt_i32_e64 s[80:81], 3, v233
	v_cndmask_b32_e64 v130, v130, v230, s[74:75]
	v_cndmask_b32_e64 v131, v131, v230, s[76:77]
	v_cndmask_b32_e64 v132, v132, v230, s[78:79]
	v_cndmask_b32_e64 v133, v133, v230, s[80:81]
	v_cmp_gt_i32_e64 s[74:75], 16, v233
	v_cmp_gt_i32_e64 s[76:77], 17, v233
	v_cmp_gt_i32_e64 s[78:79], 18, v233
	v_cmp_gt_i32_e64 s[80:81], 19, v233
	v_cndmask_b32_e64 v134, v134, v230, s[74:75]
	v_cndmask_b32_e64 v135, v135, v230, s[76:77]
	v_cndmask_b32_e64 v136, v136, v230, s[78:79]
	v_cndmask_b32_e64 v137, v137, v230, s[80:81]
	v_cmp_gt_i32_e64 s[74:75], 32, v233
	v_cmp_gt_i32_e64 s[76:77], 33, v233
	v_cmp_gt_i32_e64 s[78:79], 34, v233
	v_cmp_gt_i32_e64 s[80:81], 35, v233
	v_cndmask_b32_e64 v138, v138, v230, s[74:75]
	v_cndmask_b32_e64 v139, v139, v230, s[76:77]
	v_cndmask_b32_e64 v140, v140, v230, s[78:79]
	v_cndmask_b32_e64 v141, v141, v230, s[80:81]
	v_cmp_gt_i32_e64 s[74:75], 48, v233
	v_cmp_gt_i32_e64 s[76:77], 49, v233
	v_cmp_gt_i32_e64 s[78:79], 50, v233
	v_cmp_gt_i32_e64 s[80:81], 51, v233
	v_cndmask_b32_e64 v142, v142, v230, s[74:75]
	v_cndmask_b32_e64 v143, v143, v230, s[76:77]
	v_cndmask_b32_e64 v144, v144, v230, s[78:79]
	v_cndmask_b32_e64 v145, v145, v230, s[80:81]
	v_cmp_gt_i32_e64 s[74:75], -16, v233
	v_cmp_gt_i32_e64 s[76:77], -15, v233
	v_cmp_gt_i32_e64 s[78:79], -14, v233
	v_cmp_gt_i32_e64 s[80:81], -13, v233
	v_cndmask_b32_e64 v146, v146, v230, s[74:75]
	v_cndmask_b32_e64 v147, v147, v230, s[76:77]
	v_cndmask_b32_e64 v148, v148, v230, s[78:79]
	v_cndmask_b32_e64 v149, v149, v230, s[80:81]
	v_cmp_gt_i32_e64 s[74:75], 0, v233
	v_cmp_gt_i32_e64 s[76:77], 1, v233
	v_cmp_gt_i32_e64 s[78:79], 2, v233
	v_cmp_gt_i32_e64 s[80:81], 3, v233
	v_cndmask_b32_e64 v150, v150, v230, s[74:75]
	v_cndmask_b32_e64 v151, v151, v230, s[76:77]
	v_cndmask_b32_e64 v152, v152, v230, s[78:79]
	v_cndmask_b32_e64 v153, v153, v230, s[80:81]
	v_cmp_gt_i32_e64 s[74:75], 16, v233
	v_cmp_gt_i32_e64 s[76:77], 17, v233
	v_cmp_gt_i32_e64 s[78:79], 18, v233
	v_cmp_gt_i32_e64 s[80:81], 19, v233
	v_cndmask_b32_e64 v154, v154, v230, s[74:75]
	v_cndmask_b32_e64 v155, v155, v230, s[76:77]
	v_cndmask_b32_e64 v156, v156, v230, s[78:79]
	v_cndmask_b32_e64 v157, v157, v230, s[80:81]
	v_cmp_gt_i32_e64 s[74:75], 32, v233
	v_cmp_gt_i32_e64 s[76:77], 33, v233
	v_cmp_gt_i32_e64 s[78:79], 34, v233
	v_cmp_gt_i32_e64 s[80:81], 35, v233
	v_cndmask_b32_e64 v158, v158, v230, s[74:75]
	v_cndmask_b32_e64 v159, v159, v230, s[76:77]
	v_cndmask_b32_e64 v160, v160, v230, s[78:79]
	v_cndmask_b32_e64 v161, v161, v230, s[80:81]
.Ld16a_nm0:
	v_max3_f32 v234, v130, v131, v132
	v_max3_f32 v234, v234, v133, v134
	v_max3_f32 v234, v234, v135, v136
	v_max3_f32 v234, v234, v137, v138
	v_max3_f32 v234, v234, v139, v140
	v_max3_f32 v234, v234, v141, v142
	v_max3_f32 v234, v234, v143, v144
	v_max_f32_e32 v234, v234, v145
	v_max3_f32 v235, v146, v147, v148
	v_max3_f32 v235, v235, v149, v150
	v_max3_f32 v235, v235, v151, v152
	v_max3_f32 v235, v235, v153, v154
	v_max3_f32 v235, v235, v155, v156
	v_max3_f32 v235, v235, v157, v158
	v_max3_f32 v235, v235, v159, v160
	v_max_f32_e32 v235, v235, v161
	ds_bpermute_b32 v246, v224, v234
	ds_bpermute_b32 v247, v224, v235
	s_waitcnt lgkmcnt(0)
	v_max_f32_e32 v234, v234, v246
	v_max_f32_e32 v235, v235, v247
	v_mov_b32_e32 v246, v234
	v_mov_b32_e32 v247, v235
	s_nop 1
	v_permlane32_swap_b32_e32 v234, v246
	v_permlane32_swap_b32_e32 v235, v247
	v_max_f32_e32 v234, v234, v246
	v_max_f32_e32 v235, v235, v247
	v_sub_f32_e32 v246, v234, v237
	v_sub_f32_e32 v247, v235, v222
	v_max_f32_e32 v246, v246, v247
	v_mul_f32_e32 v246, 0x3db504f3, v246
	v_cmp_ge_f32_e32 vcc, s47, v246
	s_nop 3
	s_cmp_eq_u64 vcc, exec
	s_cbranch_scc0 .Ld16a_sl0
.Ld16a_fj0:
	v_fmamk_f32 v130, v130, 0x3e0293ee, v210
	v_fmamk_f32 v131, v131, 0x3e0293ee, v210
	v_fmamk_f32 v132, v132, 0x3e0293ee, v210
	v_fmamk_f32 v133, v133, 0x3e0293ee, v210
	v_fmamk_f32 v134, v134, 0x3e0293ee, v210
	v_fmamk_f32 v135, v135, 0x3e0293ee, v210
	v_fmamk_f32 v136, v136, 0x3e0293ee, v210
	v_fmamk_f32 v137, v137, 0x3e0293ee, v210
	v_fmamk_f32 v138, v138, 0x3e0293ee, v210
	v_fmamk_f32 v139, v139, 0x3e0293ee, v210
	v_fmamk_f32 v140, v140, 0x3e0293ee, v210
	v_fmamk_f32 v141, v141, 0x3e0293ee, v210
	v_fmamk_f32 v142, v142, 0x3e0293ee, v210
	v_fmamk_f32 v143, v143, 0x3e0293ee, v210
	v_fmamk_f32 v144, v144, 0x3e0293ee, v210
	v_fmamk_f32 v145, v145, 0x3e0293ee, v210
	v_fmamk_f32 v146, v146, 0x3e0293ee, v211
	v_fmamk_f32 v147, v147, 0x3e0293ee, v211
	v_fmamk_f32 v148, v148, 0x3e0293ee, v211
	v_fmamk_f32 v149, v149, 0x3e0293ee, v211
	v_fmamk_f32 v150, v150, 0x3e0293ee, v211
	v_fmamk_f32 v151, v151, 0x3e0293ee, v211
	v_fmamk_f32 v152, v152, 0x3e0293ee, v211
	v_fmamk_f32 v153, v153, 0x3e0293ee, v211
	v_fmamk_f32 v154, v154, 0x3e0293ee, v211
	v_fmamk_f32 v155, v155, 0x3e0293ee, v211
	v_fmamk_f32 v156, v156, 0x3e0293ee, v211
	v_fmamk_f32 v157, v157, 0x3e0293ee, v211
	v_fmamk_f32 v158, v158, 0x3e0293ee, v211
	v_fmamk_f32 v159, v159, 0x3e0293ee, v211
	v_fmamk_f32 v160, v160, 0x3e0293ee, v211
	v_fmamk_f32 v161, v161, 0x3e0293ee, v211
	v_exp_f32_e32 v130, v130
	v_exp_f32_e32 v131, v131
	v_exp_f32_e32 v132, v132
	v_exp_f32_e32 v133, v133
	v_exp_f32_e32 v134, v134
	v_exp_f32_e32 v135, v135
	v_exp_f32_e32 v136, v136
	v_exp_f32_e32 v137, v137
	v_exp_f32_e32 v138, v138
	v_exp_f32_e32 v139, v139
	v_exp_f32_e32 v140, v140
	v_exp_f32_e32 v141, v141
	v_exp_f32_e32 v142, v142
	v_exp_f32_e32 v143, v143
	v_exp_f32_e32 v144, v144
	v_exp_f32_e32 v145, v145
	v_exp_f32_e32 v146, v146
	v_exp_f32_e32 v147, v147
	v_exp_f32_e32 v148, v148
	v_exp_f32_e32 v149, v149
	v_exp_f32_e32 v150, v150
	v_exp_f32_e32 v151, v151
	v_exp_f32_e32 v152, v152
	v_exp_f32_e32 v153, v153
	v_exp_f32_e32 v154, v154
	v_exp_f32_e32 v155, v155
	v_exp_f32_e32 v156, v156
	v_exp_f32_e32 v157, v157
	v_exp_f32_e32 v158, v158
	v_exp_f32_e32 v159, v159
	v_exp_f32_e32 v160, v160
	v_exp_f32_e32 v161, v161
	v_add_f32_e32 v0, v0, v130
	v_add_f32_e32 v223, v223, v146
	v_add_f32_e32 v0, v0, v131
	v_add_f32_e32 v223, v223, v147
	v_add_f32_e32 v0, v0, v132
	v_add_f32_e32 v223, v223, v148
	v_add_f32_e32 v0, v0, v133
	v_add_f32_e32 v223, v223, v149
	v_add_f32_e32 v0, v0, v134
	v_add_f32_e32 v223, v223, v150
	v_add_f32_e32 v0, v0, v135
	v_add_f32_e32 v223, v223, v151
	v_add_f32_e32 v0, v0, v136
	v_add_f32_e32 v223, v223, v152
	v_add_f32_e32 v0, v0, v137
	v_add_f32_e32 v223, v223, v153
	v_add_f32_e32 v0, v0, v138
	v_add_f32_e32 v223, v223, v154
	v_add_f32_e32 v0, v0, v139
	v_add_f32_e32 v223, v223, v155
	v_add_f32_e32 v0, v0, v140
	v_add_f32_e32 v223, v223, v156
	v_add_f32_e32 v0, v0, v141
	v_add_f32_e32 v223, v223, v157
	v_add_f32_e32 v0, v0, v142
	v_add_f32_e32 v223, v223, v158
	v_add_f32_e32 v0, v0, v143
	v_add_f32_e32 v223, v223, v159
	v_add_f32_e32 v0, v0, v144
	v_add_f32_e32 v223, v223, v160
	v_add_f32_e32 v0, v0, v145
	v_add_f32_e32 v223, v223, v161
	v_cvt_pk_bf16_f32 v130, v130, v131
	v_cvt_pk_bf16_f32 v131, v132, v133
	v_cvt_pk_bf16_f32 v132, v134, v135
	v_cvt_pk_bf16_f32 v133, v136, v137
	v_cvt_pk_bf16_f32 v134, v138, v139
	v_cvt_pk_bf16_f32 v135, v140, v141
	v_cvt_pk_bf16_f32 v136, v142, v143
	v_cvt_pk_bf16_f32 v137, v144, v145
	v_cvt_pk_bf16_f32 v138, v146, v147
	v_cvt_pk_bf16_f32 v139, v148, v149
	v_cvt_pk_bf16_f32 v140, v150, v151
	v_cvt_pk_bf16_f32 v141, v152, v153
	v_cvt_pk_bf16_f32 v142, v154, v155
	v_cvt_pk_bf16_f32 v143, v156, v157
	v_cvt_pk_bf16_f32 v144, v158, v159
	v_cvt_pk_bf16_f32 v145, v160, v161
	ds_read_b64_tr_b16 v[146:147], v217 offset:0
	ds_read_b64_tr_b16 v[148:149], v217 offset:8192
	ds_read_b64_tr_b16 v[150:151], v217 offset:16384
	ds_read_b64_tr_b16 v[152:153], v217 offset:24576
	ds_read_b64_tr_b16 v[154:155], v217 offset:256
	ds_read_b64_tr_b16 v[156:157], v217 offset:8448
	ds_read_b64_tr_b16 v[158:159], v217 offset:16640
	ds_read_b64_tr_b16 v[160:161], v217 offset:24832
	s_waitcnt lgkmcnt(6)
	v_mfma_f32_16x16x32_bf16 v[2:5], v[130:133], v[146:149], v[2:5]
	v_mfma_f32_16x16x32_bf16 v[66:69], v[138:141], v[146:149], v[66:69]
	ds_read_b64_tr_b16 v[146:147], v217 offset:512
	ds_read_b64_tr_b16 v[148:149], v217 offset:8704
	s_waitcnt lgkmcnt(6)
	v_mfma_f32_16x16x32_bf16 v[2:5], v[134:137], v[150:153], v[2:5]
	v_mfma_f32_16x16x32_bf16 v[66:69], v[142:145], v[150:153], v[66:69]
	ds_read_b64_tr_b16 v[150:151], v217 offset:16896
	ds_read_b64_tr_b16 v[152:153], v217 offset:25088
	s_waitcnt lgkmcnt(6)
	v_mfma_f32_16x16x32_bf16 v[6:9], v[130:133], v[154:157], v[6:9]
	v_mfma_f32_16x16x32_bf16 v[70:73], v[138:141], v[154:157], v[70:73]
	ds_read_b64_tr_b16 v[154:155], v217 offset:768
	ds_read_b64_tr_b16 v[156:157], v217 offset:8960
	s_waitcnt lgkmcnt(6)
	v_mfma_f32_16x16x32_bf16 v[6:9], v[134:137], v[158:161], v[6:9]
	v_mfma_f32_16x16x32_bf16 v[70:73], v[142:145], v[158:161], v[70:73]
	ds_read_b64_tr_b16 v[158:159], v217 offset:17152
	ds_read_b64_tr_b16 v[160:161], v217 offset:25344
	s_waitcnt lgkmcnt(6)
	v_mfma_f32_16x16x32_bf16 v[10:13], v[130:133], v[146:149], v[10:13]
	v_mfma_f32_16x16x32_bf16 v[74:77], v[138:141], v[146:149], v[74:77]
	ds_read_b64_tr_b16 v[146:147], v217 offset:1024
	ds_read_b64_tr_b16 v[148:149], v217 offset:9216
	s_waitcnt lgkmcnt(6)
	v_mfma_f32_16x16x32_bf16 v[10:13], v[134:137], v[150:153], v[10:13]
	v_mfma_f32_16x16x32_bf16 v[74:77], v[142:145], v[150:153], v[74:77]
	ds_read_b64_tr_b16 v[150:151], v217 offset:17408
	ds_read_b64_tr_b16 v[152:153], v217 offset:25600
	s_waitcnt lgkmcnt(6)
	v_mfma_f32_16x16x32_bf16 v[14:17], v[130:133], v[154:157], v[14:17]
	v_mfma_f32_16x16x32_bf16 v[78:81], v[138:141], v[154:157], v[78:81]
	ds_read_b64_tr_b16 v[154:155], v217 offset:1280
	ds_read_b64_tr_b16 v[156:157], v217 offset:9472
	s_waitcnt lgkmcnt(6)
	v_mfma_f32_16x16x32_bf16 v[14:17], v[134:137], v[158:161], v[14:17]
	v_mfma_f32_16x16x32_bf16 v[78:81], v[142:145], v[158:161], v[78:81]
	ds_read_b64_tr_b16 v[158:159], v217 offset:17664
	ds_read_b64_tr_b16 v[160:161], v217 offset:25856
	s_waitcnt lgkmcnt(6)
	v_mfma_f32_16x16x32_bf16 v[18:21], v[130:133], v[146:149], v[18:21]
	v_mfma_f32_16x16x32_bf16 v[82:85], v[138:141], v[146:149], v[82:85]
	ds_read_b64_tr_b16 v[146:147], v217 offset:1536
	ds_read_b64_tr_b16 v[148:149], v217 offset:9728
	s_waitcnt lgkmcnt(6)
	v_mfma_f32_16x16x32_bf16 v[18:21], v[134:137], v[150:153], v[18:21]
	v_mfma_f32_16x16x32_bf16 v[82:85], v[142:145], v[150:153], v[82:85]
	ds_read_b64_tr_b16 v[150:151], v217 offset:17920
	ds_read_b64_tr_b16 v[152:153], v217 offset:26112
	s_waitcnt lgkmcnt(6)
	v_mfma_f32_16x16x32_bf16 v[22:25], v[130:133], v[154:157], v[22:25]
	v_mfma_f32_16x16x32_bf16 v[86:89], v[138:141], v[154:157], v[86:89]
	ds_read_b64_tr_b16 v[154:155], v217 offset:1792
	ds_read_b64_tr_b16 v[156:157], v217 offset:9984
	s_waitcnt lgkmcnt(6)
	v_mfma_f32_16x16x32_bf16 v[22:25], v[134:137], v[158:161], v[22:25]
	v_mfma_f32_16x16x32_bf16 v[86:89], v[142:145], v[158:161], v[86:89]
	ds_read_b64_tr_b16 v[158:159], v217 offset:18176
	ds_read_b64_tr_b16 v[160:161], v217 offset:26368
	s_waitcnt lgkmcnt(6)
	v_mfma_f32_16x16x32_bf16 v[26:29], v[130:133], v[146:149], v[26:29]
	v_mfma_f32_16x16x32_bf16 v[90:93], v[138:141], v[146:149], v[90:93]
	ds_read_b64_tr_b16 v[146:147], v217 offset:2048
	ds_read_b64_tr_b16 v[148:149], v217 offset:10240
	s_waitcnt lgkmcnt(6)
	v_mfma_f32_16x16x32_bf16 v[26:29], v[134:137], v[150:153], v[26:29]
	v_mfma_f32_16x16x32_bf16 v[90:93], v[142:145], v[150:153], v[90:93]
	ds_read_b64_tr_b16 v[150:151], v217 offset:18432
	ds_read_b64_tr_b16 v[152:153], v217 offset:26624
	s_waitcnt lgkmcnt(6)
	v_mfma_f32_16x16x32_bf16 v[30:33], v[130:133], v[154:157], v[30:33]
	v_mfma_f32_16x16x32_bf16 v[94:97], v[138:141], v[154:157], v[94:97]
	ds_read_b64_tr_b16 v[154:155], v217 offset:2304
	ds_read_b64_tr_b16 v[156:157], v217 offset:10496
	s_waitcnt lgkmcnt(6)
	v_mfma_f32_16x16x32_bf16 v[30:33], v[134:137], v[158:161], v[30:33]
	v_mfma_f32_16x16x32_bf16 v[94:97], v[142:145], v[158:161], v[94:97]
	ds_read_b64_tr_b16 v[158:159], v217 offset:18688
	ds_read_b64_tr_b16 v[160:161], v217 offset:26880
	s_waitcnt lgkmcnt(6)
	v_mfma_f32_16x16x32_bf16 v[34:37], v[130:133], v[146:149], v[34:37]
	v_mfma_f32_16x16x32_bf16 v[98:101], v[138:141], v[146:149], v[98:101]
	ds_read_b64_tr_b16 v[146:147], v217 offset:2560
	ds_read_b64_tr_b16 v[148:149], v217 offset:10752
	s_waitcnt lgkmcnt(6)
	v_mfma_f32_16x16x32_bf16 v[34:37], v[134:137], v[150:153], v[34:37]
	v_mfma_f32_16x16x32_bf16 v[98:101], v[142:145], v[150:153], v[98:101]
	ds_read_b64_tr_b16 v[150:151], v217 offset:18944
	ds_read_b64_tr_b16 v[152:153], v217 offset:27136
	s_waitcnt lgkmcnt(6)
	v_mfma_f32_16x16x32_bf16 v[38:41], v[130:133], v[154:157], v[38:41]
	v_mfma_f32_16x16x32_bf16 v[102:105], v[138:141], v[154:157], v[102:105]
	ds_read_b64_tr_b16 v[154:155], v217 offset:2816
	ds_read_b64_tr_b16 v[156:157], v217 offset:11008
	s_waitcnt lgkmcnt(6)
	v_mfma_f32_16x16x32_bf16 v[38:41], v[134:137], v[158:161], v[38:41]
	v_mfma_f32_16x16x32_bf16 v[102:105], v[142:145], v[158:161], v[102:105]
	ds_read_b64_tr_b16 v[158:159], v217 offset:19200
	ds_read_b64_tr_b16 v[160:161], v217 offset:27392
	s_waitcnt lgkmcnt(6)
	v_mfma_f32_16x16x32_bf16 v[42:45], v[130:133], v[146:149], v[42:45]
	v_mfma_f32_16x16x32_bf16 v[106:109], v[138:141], v[146:149], v[106:109]
	ds_read_b64_tr_b16 v[146:147], v217 offset:3072
	ds_read_b64_tr_b16 v[148:149], v217 offset:11264
	s_waitcnt lgkmcnt(6)
	v_mfma_f32_16x16x32_bf16 v[42:45], v[134:137], v[150:153], v[42:45]
	v_mfma_f32_16x16x32_bf16 v[106:109], v[142:145], v[150:153], v[106:109]
	ds_read_b64_tr_b16 v[150:151], v217 offset:19456
	ds_read_b64_tr_b16 v[152:153], v217 offset:27648
	s_waitcnt lgkmcnt(6)
	v_mfma_f32_16x16x32_bf16 v[46:49], v[130:133], v[154:157], v[46:49]
	v_mfma_f32_16x16x32_bf16 v[110:113], v[138:141], v[154:157], v[110:113]
	ds_read_b64_tr_b16 v[154:155], v217 offset:3328
	ds_read_b64_tr_b16 v[156:157], v217 offset:11520
	s_waitcnt lgkmcnt(6)
	v_mfma_f32_16x16x32_bf16 v[46:49], v[134:137], v[158:161], v[46:49]
	v_mfma_f32_16x16x32_bf16 v[110:113], v[142:145], v[158:161], v[110:113]
	ds_read_b64_tr_b16 v[158:159], v217 offset:19712
	ds_read_b64_tr_b16 v[160:161], v217 offset:27904
	s_waitcnt lgkmcnt(6)
	v_mfma_f32_16x16x32_bf16 v[50:53], v[130:133], v[146:149], v[50:53]
	v_mfma_f32_16x16x32_bf16 v[114:117], v[138:141], v[146:149], v[114:117]
	ds_read_b64_tr_b16 v[146:147], v217 offset:3584
	ds_read_b64_tr_b16 v[148:149], v217 offset:11776
	s_waitcnt lgkmcnt(6)
	v_mfma_f32_16x16x32_bf16 v[50:53], v[134:137], v[150:153], v[50:53]
	v_mfma_f32_16x16x32_bf16 v[114:117], v[142:145], v[150:153], v[114:117]
	ds_read_b64_tr_b16 v[150:151], v217 offset:19968
	ds_read_b64_tr_b16 v[152:153], v217 offset:28160
	s_waitcnt lgkmcnt(6)
	v_mfma_f32_16x16x32_bf16 v[54:57], v[130:133], v[154:157], v[54:57]
	v_mfma_f32_16x16x32_bf16 v[118:121], v[138:141], v[154:157], v[118:121]
	ds_read_b64_tr_b16 v[154:155], v217 offset:3840
	ds_read_b64_tr_b16 v[156:157], v217 offset:12032
	s_waitcnt lgkmcnt(6)
	v_mfma_f32_16x16x32_bf16 v[54:57], v[134:137], v[158:161], v[54:57]
	v_mfma_f32_16x16x32_bf16 v[118:121], v[142:145], v[158:161], v[118:121]
	ds_read_b64_tr_b16 v[158:159], v217 offset:20224
	ds_read_b64_tr_b16 v[160:161], v217 offset:28416
	s_waitcnt lgkmcnt(6)
	v_mfma_f32_16x16x32_bf16 v[58:61], v[130:133], v[146:149], v[58:61]
	v_mfma_f32_16x16x32_bf16 v[122:125], v[138:141], v[146:149], v[122:125]
	s_waitcnt lgkmcnt(4)
	v_mfma_f32_16x16x32_bf16 v[58:61], v[134:137], v[150:153], v[58:61]
	v_mfma_f32_16x16x32_bf16 v[122:125], v[142:145], v[150:153], v[122:125]
	s_waitcnt lgkmcnt(2)
	v_mfma_f32_16x16x32_bf16 v[62:65], v[130:133], v[154:157], v[62:65]
	v_mfma_f32_16x16x32_bf16 v[126:129], v[138:141], v[154:157], v[126:129]
	s_waitcnt lgkmcnt(0)
	v_mfma_f32_16x16x32_bf16 v[62:65], v[134:137], v[158:161], v[62:65]
	v_mfma_f32_16x16x32_bf16 v[126:129], v[142:145], v[158:161], v[126:129]
	s_branch .Ld16a_end0
.Ld16a_sl0:
	v_max_f32_e32 v234, v237, v234
	v_max_f32_e32 v235, v222, v235
	v_sub_f32_e32 v246, v237, v234
	v_sub_f32_e32 v247, v222, v235
	v_mul_f32_e32 v246, 0x3e0293ee, v246
	v_mul_f32_e32 v247, 0x3e0293ee, v247
	v_exp_f32_e32 v246, v246
	v_exp_f32_e32 v247, v247
	v_mov_b32_e32 v237, v234
	v_mov_b32_e32 v222, v235
	v_mul_f32_e32 v210, 0xbe0293ee, v234
	v_mul_f32_e32 v211, 0xbe0293ee, v235
	v_mul_f32_e32 v0, v0, v246
	v_mul_f32_e32 v223, v223, v247
	s_and_saveexec_b64 s[76:77], s[0:1]
	ds_write_b32 v232, v246 offset:128
	ds_write_b32 v232, v247 offset:192
	s_or_b64 exec, exec, s[76:77]
	s_waitcnt lgkmcnt(0)
	ds_read_b128 v[238:241], v231 offset:128
	ds_read_b128 v[242:245], v231 offset:192
	s_waitcnt lgkmcnt(0)
	v_pk_mul_f32 v[2:3], v[2:3], v[238:239]
	v_pk_mul_f32 v[4:5], v[4:5], v[240:241]
	v_pk_mul_f32 v[6:7], v[6:7], v[238:239]
	v_pk_mul_f32 v[8:9], v[8:9], v[240:241]
	v_pk_mul_f32 v[10:11], v[10:11], v[238:239]
	v_pk_mul_f32 v[12:13], v[12:13], v[240:241]
	v_pk_mul_f32 v[14:15], v[14:15], v[238:239]
	v_pk_mul_f32 v[16:17], v[16:17], v[240:241]
	v_pk_mul_f32 v[18:19], v[18:19], v[238:239]
	v_pk_mul_f32 v[20:21], v[20:21], v[240:241]
	v_pk_mul_f32 v[22:23], v[22:23], v[238:239]
	v_pk_mul_f32 v[24:25], v[24:25], v[240:241]
	v_pk_mul_f32 v[26:27], v[26:27], v[238:239]
	v_pk_mul_f32 v[28:29], v[28:29], v[240:241]
	v_pk_mul_f32 v[30:31], v[30:31], v[238:239]
	v_pk_mul_f32 v[32:33], v[32:33], v[240:241]
	v_pk_mul_f32 v[34:35], v[34:35], v[238:239]
	v_pk_mul_f32 v[36:37], v[36:37], v[240:241]
	v_pk_mul_f32 v[38:39], v[38:39], v[238:239]
	v_pk_mul_f32 v[40:41], v[40:41], v[240:241]
	v_pk_mul_f32 v[42:43], v[42:43], v[238:239]
	v_pk_mul_f32 v[44:45], v[44:45], v[240:241]
	v_pk_mul_f32 v[46:47], v[46:47], v[238:239]
	v_pk_mul_f32 v[48:49], v[48:49], v[240:241]
	v_pk_mul_f32 v[50:51], v[50:51], v[238:239]
	v_pk_mul_f32 v[52:53], v[52:53], v[240:241]
	v_pk_mul_f32 v[54:55], v[54:55], v[238:239]
	v_pk_mul_f32 v[56:57], v[56:57], v[240:241]
	v_pk_mul_f32 v[58:59], v[58:59], v[238:239]
	v_pk_mul_f32 v[60:61], v[60:61], v[240:241]
	v_pk_mul_f32 v[62:63], v[62:63], v[238:239]
	v_pk_mul_f32 v[64:65], v[64:65], v[240:241]
	v_pk_mul_f32 v[66:67], v[66:67], v[242:243]
	v_pk_mul_f32 v[68:69], v[68:69], v[244:245]
	v_pk_mul_f32 v[70:71], v[70:71], v[242:243]
	v_pk_mul_f32 v[72:73], v[72:73], v[244:245]
	v_pk_mul_f32 v[74:75], v[74:75], v[242:243]
	v_pk_mul_f32 v[76:77], v[76:77], v[244:245]
	v_pk_mul_f32 v[78:79], v[78:79], v[242:243]
	v_pk_mul_f32 v[80:81], v[80:81], v[244:245]
	v_pk_mul_f32 v[82:83], v[82:83], v[242:243]
	v_pk_mul_f32 v[84:85], v[84:85], v[244:245]
	v_pk_mul_f32 v[86:87], v[86:87], v[242:243]
	v_pk_mul_f32 v[88:89], v[88:89], v[244:245]
	v_pk_mul_f32 v[90:91], v[90:91], v[242:243]
	v_pk_mul_f32 v[92:93], v[92:93], v[244:245]
	v_pk_mul_f32 v[94:95], v[94:95], v[242:243]
	v_pk_mul_f32 v[96:97], v[96:97], v[244:245]
	v_pk_mul_f32 v[98:99], v[98:99], v[242:243]
	v_pk_mul_f32 v[100:101], v[100:101], v[244:245]
	v_pk_mul_f32 v[102:103], v[102:103], v[242:243]
	v_pk_mul_f32 v[104:105], v[104:105], v[244:245]
	v_pk_mul_f32 v[106:107], v[106:107], v[242:243]
	v_pk_mul_f32 v[108:109], v[108:109], v[244:245]
	v_pk_mul_f32 v[110:111], v[110:111], v[242:243]
	v_pk_mul_f32 v[112:113], v[112:113], v[244:245]
	v_pk_mul_f32 v[114:115], v[114:115], v[242:243]
	v_pk_mul_f32 v[116:117], v[116:117], v[244:245]
	v_pk_mul_f32 v[118:119], v[118:119], v[242:243]
	v_pk_mul_f32 v[120:121], v[120:121], v[244:245]
	v_pk_mul_f32 v[122:123], v[122:123], v[242:243]
	v_pk_mul_f32 v[124:125], v[124:125], v[244:245]
	v_pk_mul_f32 v[126:127], v[126:127], v[242:243]
	v_pk_mul_f32 v[128:129], v[128:129], v[244:245]
	s_branch .Ld16a_fj0
.Ld16a_end0:
	s_waitcnt vmcnt(0)
	s_cmp_gt_u32 s57, s55
	s_cselect_b64 s[36:37], -1, 0
	s_and_b64 vcc, exec, s[36:37]
	s_waitcnt vmcnt(0) lgkmcnt(0)
	s_barrier
	s_cbranch_vccnz .LBB0_798
	s_mov_b64 s[38:39], src_shared_base
	s_cmp_lg_u32 0, -1
	s_cselect_b32 s38, 0, 0
	s_cselect_b32 s39, s39, 0
	s_add_u32 s38, s38, 0x10000
	s_addc_u32 s39, s39, 0
	s_cmp_lg_u64 s[38:39], 0
	s_cselect_b32 s38, s38, -1
	s_add_i32 s38, s38, s53
	v_lshl_add_u64 v[130:131], v[206:207], 0, s[20:21]
	s_mov_b32 m0, s38
	s_nop 0
	global_load_lds_dwordx4 v[130:131], off
	v_lshl_add_u64 v[130:131], v[204:205], 0, s[20:21]
	s_add_i32 m0, s38, 0x400
	s_add_i32 s38, s54, 0
	global_load_lds_dwordx4 v[130:131], off
	v_lshl_add_u64 v[130:131], v[202:203], 0, s[22:23]
	s_mov_b32 m0, s38
	s_nop 0
	global_load_lds_dwordx4 v[130:131], off
	v_lshl_add_u64 v[130:131], v[202:203], 0, s[24:25]
	s_add_i32 m0, s38, 0x400
	s_nop 0
	global_load_lds_dwordx4 v[130:131], off
	v_lshl_add_u64 v[130:131], v[202:203], 0, s[26:27]
	s_add_i32 m0, s38, 0x800
	s_nop 0
	global_load_lds_dwordx4 v[130:131], off
	v_lshl_add_u64 v[130:131], v[202:203], 0, s[28:29]
	s_add_i32 m0, s38, 0xc00
	s_nop 0
	global_load_lds_dwordx4 v[130:131], off
.LBB0_798:
	s_sub_i32 s73, s56, 94
	s_cmp_gt_i32 s73, s4
	s_cbranch_scc1 .Ld16a_end1
	ds_read_b128 v[238:241], v218 offset:16384
	ds_read_b128 v[242:245], v219 offset:16384
	ds_read_b128 v[246:249], v218 offset:16512
	s_waitcnt lgkmcnt(2)
	v_mfma_f32_16x16x32_bf16 v[130:133], v[238:241], v[162:165], 0
	v_mfma_f32_16x16x32_bf16 v[146:149], v[238:241], v[178:181], 0
	ds_read_b128 v[238:241], v219 offset:16512
	s_waitcnt lgkmcnt(2)
	v_mfma_f32_16x16x32_bf16 v[130:133], v[242:245], v[166:169], v[130:133]
	v_mfma_f32_16x16x32_bf16 v[146:149], v[242:245], v[182:185], v[146:149]
	ds_read_b128 v[242:245], v218 offset:20480
	s_waitcnt lgkmcnt(2)
	v_mfma_f32_16x16x32_bf16 v[130:133], v[246:249], v[170:173], v[130:133]
	v_mfma_f32_16x16x32_bf16 v[146:149], v[246:249], v[186:189], v[146:149]
	ds_read_b128 v[246:249], v219 offset:20480
	s_waitcnt lgkmcnt(2)
	v_mfma_f32_16x16x32_bf16 v[130:133], v[238:241], v[174:177], v[130:133]
	v_mfma_f32_16x16x32_bf16 v[146:149], v[238:241], v[190:193], v[146:149]
	ds_read_b128 v[238:241], v218 offset:20608
	s_waitcnt lgkmcnt(2)
	v_mfma_f32_16x16x32_bf16 v[134:137], v[242:245], v[162:165], 0
	v_mfma_f32_16x16x32_bf16 v[150:153], v[242:245], v[178:181], 0
	ds_read_b128 v[242:245], v219 offset:20608
	s_waitcnt lgkmcnt(2)
	v_mfma_f32_16x16x32_bf16 v[134:137], v[246:249], v[166:169], v[134:137]
	v_mfma_f32_16x16x32_bf16 v[150:153], v[246:249], v[182:185], v[150:153]
	ds_read_b128 v[246:249], v218 offset:24576
	s_waitcnt lgkmcnt(2)
	v_mfma_f32_16x16x32_bf16 v[134:137], v[238:241], v[170:173], v[134:137]
	v_mfma_f32_16x16x32_bf16 v[150:153], v[238:241], v[186:189], v[150:153]
	ds_read_b128 v[238:241], v219 offset:24576
	s_waitcnt lgkmcnt(2)
	v_mfma_f32_16x16x32_bf16 v[134:137], v[242:245], v[174:177], v[134:137]
	v_mfma_f32_16x16x32_bf16 v[150:153], v[242:245], v[190:193], v[150:153]
	ds_read_b128 v[242:245], v218 offset:24704
	s_waitcnt lgkmcnt(2)
	v_mfma_f32_16x16x32_bf16 v[138:141], v[246:249], v[162:165], 0
	v_mfma_f32_16x16x32_bf16 v[154:157], v[246:249], v[178:181], 0
	ds_read_b128 v[246:249], v219 offset:24704
	s_waitcnt lgkmcnt(2)
	v_mfma_f32_16x16x32_bf16 v[138:141], v[238:241], v[166:169], v[138:141]
	v_mfma_f32_16x16x32_bf16 v[154:157], v[238:241], v[182:185], v[154:157]
	ds_read_b128 v[238:241], v218 offset:28672
	s_waitcnt lgkmcnt(2)
	v_mfma_f32_16x16x32_bf16 v[138:141], v[242:245], v[170:173], v[138:141]
	v_mfma_f32_16x16x32_bf16 v[154:157], v[242:245], v[186:189], v[154:157]
	ds_read_b128 v[242:245], v219 offset:28672
	s_waitcnt lgkmcnt(2)
	v_mfma_f32_16x16x32_bf16 v[138:141], v[246:249], v[174:177], v[138:141]
	v_mfma_f32_16x16x32_bf16 v[154:157], v[246:249], v[190:193], v[154:157]
	ds_read_b128 v[246:249], v218 offset:28800
	s_waitcnt lgkmcnt(2)
	v_mfma_f32_16x16x32_bf16 v[142:145], v[238:241], v[162:165], 0
	v_mfma_f32_16x16x32_bf16 v[158:161], v[238:241], v[178:181], 0
	ds_read_b128 v[238:241], v219 offset:28800
	s_waitcnt lgkmcnt(2)
	v_mfma_f32_16x16x32_bf16 v[142:145], v[242:245], v[166:169], v[142:145]
	v_mfma_f32_16x16x32_bf16 v[158:161], v[242:245], v[182:185], v[158:161]
	s_waitcnt lgkmcnt(1)
	v_mfma_f32_16x16x32_bf16 v[142:145], v[246:249], v[170:173], v[142:145]
	v_mfma_f32_16x16x32_bf16 v[158:161], v[246:249], v[186:189], v[158:161]
	s_waitcnt lgkmcnt(0)
	v_mfma_f32_16x16x32_bf16 v[142:145], v[238:241], v[174:177], v[142:145]
	v_mfma_f32_16x16x32_bf16 v[158:161], v[238:241], v[190:193], v[158:161]
	s_nop 7
	s_nop 1
	s_cmp_le_i32 s56, s4
	s_cbranch_scc1 .Ld16a_nm1
	v_subrev_u32_e32 v246, 64, v233
	v_cmp_gt_i32_e64 s[74:75], 0, v246
	v_cmp_gt_i32_e64 s[76:77], 1, v246
	v_cmp_gt_i32_e64 s[78:79], 2, v246
	v_cmp_gt_i32_e64 s[80:81], 3, v246
	v_cndmask_b32_e64 v130, v130, v230, s[74:75]
	v_cndmask_b32_e64 v131, v131, v230, s[76:77]
	v_cndmask_b32_e64 v132, v132, v230, s[78:79]
	v_cndmask_b32_e64 v133, v133, v230, s[80:81]
	v_cmp_gt_i32_e64 s[74:75], 16, v246
	v_cmp_gt_i32_e64 s[76:77], 17, v246
	v_cmp_gt_i32_e64 s[78:79], 18, v246
	v_cmp_gt_i32_e64 s[80:81], 19, v246
	v_cndmask_b32_e64 v134, v134, v230, s[74:75]
	v_cndmask_b32_e64 v135, v135, v230, s[76:77]
	v_cndmask_b32_e64 v136, v136, v230, s[78:79]
	v_cndmask_b32_e64 v137, v137, v230, s[80:81]
	v_cmp_gt_i32_e64 s[74:75], 32, v246
	v_cmp_gt_i32_e64 s[76:77], 33, v246
	v_cmp_gt_i32_e64 s[78:79], 34, v246
	v_cmp_gt_i32_e64 s[80:81], 35, v246
	v_cndmask_b32_e64 v138, v138, v230, s[74:75]
	v_cndmask_b32_e64 v139, v139, v230, s[76:77]
	v_cndmask_b32_e64 v140, v140, v230, s[78:79]
	v_cndmask_b32_e64 v141, v141, v230, s[80:81]
	v_cmp_gt_i32_e64 s[74:75], 48, v246
	v_cmp_gt_i32_e64 s[76:77], 49, v246
	v_cmp_gt_i32_e64 s[78:79], 50, v246
	v_cmp_gt_i32_e64 s[80:81], 51, v246
	v_cndmask_b32_e64 v142, v142, v230, s[74:75]
	v_cndmask_b32_e64 v143, v143, v230, s[76:77]
	v_cndmask_b32_e64 v144, v144, v230, s[78:79]
	v_cndmask_b32_e64 v145, v145, v230, s[80:81]
	v_cmp_gt_i32_e64 s[74:75], -16, v246
	v_cmp_gt_i32_e64 s[76:77], -15, v246
	v_cmp_gt_i32_e64 s[78:79], -14, v246
	v_cmp_gt_i32_e64 s[80:81], -13, v246
	v_cndmask_b32_e64 v146, v146, v230, s[74:75]
	v_cndmask_b32_e64 v147, v147, v230, s[76:77]
	v_cndmask_b32_e64 v148, v148, v230, s[78:79]
	v_cndmask_b32_e64 v149, v149, v230, s[80:81]
	v_cmp_gt_i32_e64 s[74:75], 0, v246
	v_cmp_gt_i32_e64 s[76:77], 1, v246
	v_cmp_gt_i32_e64 s[78:79], 2, v246
	v_cmp_gt_i32_e64 s[80:81], 3, v246
	v_cndmask_b32_e64 v150, v150, v230, s[74:75]
	v_cndmask_b32_e64 v151, v151, v230, s[76:77]
	v_cndmask_b32_e64 v152, v152, v230, s[78:79]
	v_cndmask_b32_e64 v153, v153, v230, s[80:81]
	v_cmp_gt_i32_e64 s[74:75], 16, v246
	v_cmp_gt_i32_e64 s[76:77], 17, v246
	v_cmp_gt_i32_e64 s[78:79], 18, v246
	v_cmp_gt_i32_e64 s[80:81], 19, v246
	v_cndmask_b32_e64 v154, v154, v230, s[74:75]
	v_cndmask_b32_e64 v155, v155, v230, s[76:77]
	v_cndmask_b32_e64 v156, v156, v230, s[78:79]
	v_cndmask_b32_e64 v157, v157, v230, s[80:81]
	v_cmp_gt_i32_e64 s[74:75], 32, v246
	v_cmp_gt_i32_e64 s[76:77], 33, v246
	v_cmp_gt_i32_e64 s[78:79], 34, v246
	v_cmp_gt_i32_e64 s[80:81], 35, v246
	v_cndmask_b32_e64 v158, v158, v230, s[74:75]
	v_cndmask_b32_e64 v159, v159, v230, s[76:77]
	v_cndmask_b32_e64 v160, v160, v230, s[78:79]
	v_cndmask_b32_e64 v161, v161, v230, s[80:81]

.Ld16a_fj1:
	v_fmamk_f32 v130, v130, 0x3e0293ee, v210
	v_fmamk_f32 v131, v131, 0x3e0293ee, v210
	v_fmamk_f32 v132, v132, 0x3e0293ee, v210
	v_fmamk_f32 v133, v133, 0x3e0293ee, v210
	v_fmamk_f32 v134, v134, 0x3e0293ee, v210
	v_fmamk_f32 v135, v135, 0x3e0293ee, v210
	v_fmamk_f32 v136, v136, 0x3e0293ee, v210
	v_fmamk_f32 v137, v137, 0x3e0293ee, v210
	v_fmamk_f32 v138, v138, 0x3e0293ee, v210
	v_fmamk_f32 v139, v139, 0x3e0293ee, v210
	v_fmamk_f32 v140, v140, 0x3e0293ee, v210
	v_fmamk_f32 v141, v141, 0x3e0293ee, v210
	v_fmamk_f32 v142, v142, 0x3e0293ee, v210
	v_fmamk_f32 v143, v143, 0x3e0293ee, v210
	v_fmamk_f32 v144, v144, 0x3e0293ee, v210
	v_fmamk_f32 v145, v145, 0x3e0293ee, v210
	v_fmamk_f32 v146, v146, 0x3e0293ee, v211
	v_fmamk_f32 v147, v147, 0x3e0293ee, v211
	v_fmamk_f32 v148, v148, 0x3e0293ee, v211
	v_fmamk_f32 v149, v149, 0x3e0293ee, v211
	v_fmamk_f32 v150, v150, 0x3e0293ee, v211
	v_fmamk_f32 v151, v151, 0x3e0293ee, v211
	v_fmamk_f32 v152, v152, 0x3e0293ee, v211
	v_fmamk_f32 v153, v153, 0x3e0293ee, v211
	v_fmamk_f32 v154, v154, 0x3e0293ee, v211
	v_fmamk_f32 v155, v155, 0x3e0293ee, v211
	v_fmamk_f32 v156, v156, 0x3e0293ee, v211
	v_fmamk_f32 v157, v157, 0x3e0293ee, v211
	v_fmamk_f32 v158, v158, 0x3e0293ee, v211
	v_fmamk_f32 v159, v159, 0x3e0293ee, v211
	v_fmamk_f32 v160, v160, 0x3e0293ee, v211
	v_fmamk_f32 v161, v161, 0x3e0293ee, v211
	v_exp_f32_e32 v130, v130
	v_exp_f32_e32 v131, v131
	v_exp_f32_e32 v132, v132
	v_exp_f32_e32 v133, v133
	v_exp_f32_e32 v134, v134
	v_exp_f32_e32 v135, v135
	v_exp_f32_e32 v136, v136
	v_exp_f32_e32 v137, v137
	v_exp_f32_e32 v138, v138
	v_exp_f32_e32 v139, v139
	v_exp_f32_e32 v140, v140
	v_exp_f32_e32 v141, v141
	v_exp_f32_e32 v142, v142
	v_exp_f32_e32 v143, v143
	v_exp_f32_e32 v144, v144
	v_exp_f32_e32 v145, v145
	v_exp_f32_e32 v146, v146
	v_exp_f32_e32 v147, v147
	v_exp_f32_e32 v148, v148
	v_exp_f32_e32 v149, v149
	v_exp_f32_e32 v150, v150
	v_exp_f32_e32 v151, v151
	v_exp_f32_e32 v152, v152
	v_exp_f32_e32 v153, v153
	v_exp_f32_e32 v154, v154
	v_exp_f32_e32 v155, v155
	v_exp_f32_e32 v156, v156
	v_exp_f32_e32 v157, v157
	v_exp_f32_e32 v158, v158
	v_exp_f32_e32 v159, v159
	v_exp_f32_e32 v160, v160
	v_exp_f32_e32 v161, v161
	v_add_f32_e32 v0, v0, v130
	v_add_f32_e32 v223, v223, v146
	v_add_f32_e32 v0, v0, v131
	v_add_f32_e32 v223, v223, v147
	v_add_f32_e32 v0, v0, v132
	v_add_f32_e32 v223, v223, v148
	v_add_f32_e32 v0, v0, v133
	v_add_f32_e32 v223, v223, v149
	v_add_f32_e32 v0, v0, v134
	v_add_f32_e32 v223, v223, v150
	v_add_f32_e32 v0, v0, v135
	v_add_f32_e32 v223, v223, v151
	v_add_f32_e32 v0, v0, v136
	v_add_f32_e32 v223, v223, v152
	v_add_f32_e32 v0, v0, v137
	v_add_f32_e32 v223, v223, v153
	v_add_f32_e32 v0, v0, v138
	v_add_f32_e32 v223, v223, v154
	v_add_f32_e32 v0, v0, v139
	v_add_f32_e32 v223, v223, v155
	v_add_f32_e32 v0, v0, v140
	v_add_f32_e32 v223, v223, v156
	v_add_f32_e32 v0, v0, v141
	v_add_f32_e32 v223, v223, v157
	v_add_f32_e32 v0, v0, v142
	v_add_f32_e32 v223, v223, v158
	v_add_f32_e32 v0, v0, v143
	v_add_f32_e32 v223, v223, v159
	v_add_f32_e32 v0, v0, v144
	v_add_f32_e32 v223, v223, v160
	v_add_f32_e32 v0, v0, v145
	v_add_f32_e32 v223, v223, v161
	v_cvt_pk_bf16_f32 v130, v130, v131
	v_cvt_pk_bf16_f32 v131, v132, v133
	v_cvt_pk_bf16_f32 v132, v134, v135
	v_cvt_pk_bf16_f32 v133, v136, v137
	v_cvt_pk_bf16_f32 v134, v138, v139
	v_cvt_pk_bf16_f32 v135, v140, v141
	v_cvt_pk_bf16_f32 v136, v142, v143
	v_cvt_pk_bf16_f32 v137, v144, v145
	v_cvt_pk_bf16_f32 v138, v146, v147
	v_cvt_pk_bf16_f32 v139, v148, v149
	v_cvt_pk_bf16_f32 v140, v150, v151
	v_cvt_pk_bf16_f32 v141, v152, v153
	v_cvt_pk_bf16_f32 v142, v154, v155
	v_cvt_pk_bf16_f32 v143, v156, v157
	v_cvt_pk_bf16_f32 v144, v158, v159
	v_cvt_pk_bf16_f32 v145, v160, v161
	ds_read_b64_tr_b16 v[146:147], v217 offset:32768
	ds_read_b64_tr_b16 v[148:149], v217 offset:40960
	ds_read_b64_tr_b16 v[150:151], v217 offset:49152
	ds_read_b64_tr_b16 v[152:153], v217 offset:57344
	ds_read_b64_tr_b16 v[154:155], v217 offset:33024
	ds_read_b64_tr_b16 v[156:157], v217 offset:41216
	ds_read_b64_tr_b16 v[158:159], v217 offset:49408
	ds_read_b64_tr_b16 v[160:161], v217 offset:57600
	s_waitcnt lgkmcnt(6)
	v_mfma_f32_16x16x32_bf16 v[2:5], v[130:133], v[146:149], v[2:5]
	v_mfma_f32_16x16x32_bf16 v[66:69], v[138:141], v[146:149], v[66:69]
	ds_read_b64_tr_b16 v[146:147], v217 offset:33280
	ds_read_b64_tr_b16 v[148:149], v217 offset:41472
	s_waitcnt lgkmcnt(6)
	v_mfma_f32_16x16x32_bf16 v[2:5], v[134:137], v[150:153], v[2:5]
	v_mfma_f32_16x16x32_bf16 v[66:69], v[142:145], v[150:153], v[66:69]
	ds_read_b64_tr_b16 v[150:151], v217 offset:49664
	ds_read_b64_tr_b16 v[152:153], v217 offset:57856
	s_waitcnt lgkmcnt(6)
	v_mfma_f32_16x16x32_bf16 v[6:9], v[130:133], v[154:157], v[6:9]
	v_mfma_f32_16x16x32_bf16 v[70:73], v[138:141], v[154:157], v[70:73]
	ds_read_b64_tr_b16 v[154:155], v217 offset:33536
	ds_read_b64_tr_b16 v[156:157], v217 offset:41728
	s_waitcnt lgkmcnt(6)
	v_mfma_f32_16x16x32_bf16 v[6:9], v[134:137], v[158:161], v[6:9]
	v_mfma_f32_16x16x32_bf16 v[70:73], v[142:145], v[158:161], v[70:73]
	ds_read_b64_tr_b16 v[158:159], v217 offset:49920
	ds_read_b64_tr_b16 v[160:161], v217 offset:58112
	s_waitcnt lgkmcnt(6)
	v_mfma_f32_16x16x32_bf16 v[10:13], v[130:133], v[146:149], v[10:13]
	v_mfma_f32_16x16x32_bf16 v[74:77], v[138:141], v[146:149], v[74:77]
	ds_read_b64_tr_b16 v[146:147], v217 offset:33792
	ds_read_b64_tr_b16 v[148:149], v217 offset:41984
	s_waitcnt lgkmcnt(6)
	v_mfma_f32_16x16x32_bf16 v[10:13], v[134:137], v[150:153], v[10:13]
	v_mfma_f32_16x16x32_bf16 v[74:77], v[142:145], v[150:153], v[74:77]
	ds_read_b64_tr_b16 v[150:151], v217 offset:50176
	ds_read_b64_tr_b16 v[152:153], v217 offset:58368
	s_waitcnt lgkmcnt(6)
	v_mfma_f32_16x16x32_bf16 v[14:17], v[130:133], v[154:157], v[14:17]
	v_mfma_f32_16x16x32_bf16 v[78:81], v[138:141], v[154:157], v[78:81]
	ds_read_b64_tr_b16 v[154:155], v217 offset:34048
	ds_read_b64_tr_b16 v[156:157], v217 offset:42240
	s_waitcnt lgkmcnt(6)
	v_mfma_f32_16x16x32_bf16 v[14:17], v[134:137], v[158:161], v[14:17]
	v_mfma_f32_16x16x32_bf16 v[78:81], v[142:145], v[158:161], v[78:81]
	ds_read_b64_tr_b16 v[158:159], v217 offset:50432
	ds_read_b64_tr_b16 v[160:161], v217 offset:58624
	s_waitcnt lgkmcnt(6)
	v_mfma_f32_16x16x32_bf16 v[18:21], v[130:133], v[146:149], v[18:21]
	v_mfma_f32_16x16x32_bf16 v[82:85], v[138:141], v[146:149], v[82:85]
	ds_read_b64_tr_b16 v[146:147], v217 offset:34304
	ds_read_b64_tr_b16 v[148:149], v217 offset:42496
	s_waitcnt lgkmcnt(6)
	v_mfma_f32_16x16x32_bf16 v[18:21], v[134:137], v[150:153], v[18:21]
	v_mfma_f32_16x16x32_bf16 v[82:85], v[142:145], v[150:153], v[82:85]
	ds_read_b64_tr_b16 v[150:151], v217 offset:50688
	ds_read_b64_tr_b16 v[152:153], v217 offset:58880
	s_waitcnt lgkmcnt(6)
	v_mfma_f32_16x16x32_bf16 v[22:25], v[130:133], v[154:157], v[22:25]
	v_mfma_f32_16x16x32_bf16 v[86:89], v[138:141], v[154:157], v[86:89]
	ds_read_b64_tr_b16 v[154:155], v217 offset:34560
	ds_read_b64_tr_b16 v[156:157], v217 offset:42752
	s_waitcnt lgkmcnt(6)
	v_mfma_f32_16x16x32_bf16 v[22:25], v[134:137], v[158:161], v[22:25]
	v_mfma_f32_16x16x32_bf16 v[86:89], v[142:145], v[158:161], v[86:89]
	ds_read_b64_tr_b16 v[158:159], v217 offset:50944
	ds_read_b64_tr_b16 v[160:161], v217 offset:59136
	s_waitcnt lgkmcnt(6)
	v_mfma_f32_16x16x32_bf16 v[26:29], v[130:133], v[146:149], v[26:29]
	v_mfma_f32_16x16x32_bf16 v[90:93], v[138:141], v[146:149], v[90:93]
	ds_read_b64_tr_b16 v[146:147], v217 offset:34816
	ds_read_b64_tr_b16 v[148:149], v217 offset:43008
	s_waitcnt lgkmcnt(6)
	v_mfma_f32_16x16x32_bf16 v[26:29], v[134:137], v[150:153], v[26:29]
	v_mfma_f32_16x16x32_bf16 v[90:93], v[142:145], v[150:153], v[90:93]
	ds_read_b64_tr_b16 v[150:151], v217 offset:51200
	ds_read_b64_tr_b16 v[152:153], v217 offset:59392
	s_waitcnt lgkmcnt(6)
	v_mfma_f32_16x16x32_bf16 v[30:33], v[130:133], v[154:157], v[30:33]
	v_mfma_f32_16x16x32_bf16 v[94:97], v[138:141], v[154:157], v[94:97]
	ds_read_b64_tr_b16 v[154:155], v217 offset:35072
	ds_read_b64_tr_b16 v[156:157], v217 offset:43264
	s_waitcnt lgkmcnt(6)
	v_mfma_f32_16x16x32_bf16 v[30:33], v[134:137], v[158:161], v[30:33]
	v_mfma_f32_16x16x32_bf16 v[94:97], v[142:145], v[158:161], v[94:97]
	ds_read_b64_tr_b16 v[158:159], v217 offset:51456
	ds_read_b64_tr_b16 v[160:161], v217 offset:59648
	s_waitcnt lgkmcnt(6)
	v_mfma_f32_16x16x32_bf16 v[34:37], v[130:133], v[146:149], v[34:37]
	v_mfma_f32_16x16x32_bf16 v[98:101], v[138:141], v[146:149], v[98:101]
	ds_read_b64_tr_b16 v[146:147], v217 offset:35328
	ds_read_b64_tr_b16 v[148:149], v217 offset:43520
	s_waitcnt lgkmcnt(6)
	v_mfma_f32_16x16x32_bf16 v[34:37], v[134:137], v[150:153], v[34:37]
	v_mfma_f32_16x16x32_bf16 v[98:101], v[142:145], v[150:153], v[98:101]
	ds_read_b64_tr_b16 v[150:151], v217 offset:51712
	ds_read_b64_tr_b16 v[152:153], v217 offset:59904
	s_waitcnt lgkmcnt(6)
	v_mfma_f32_16x16x32_bf16 v[38:41], v[130:133], v[154:157], v[38:41]
	v_mfma_f32_16x16x32_bf16 v[102:105], v[138:141], v[154:157], v[102:105]
	ds_read_b64_tr_b16 v[154:155], v217 offset:35584
	ds_read_b64_tr_b16 v[156:157], v217 offset:43776
	s_waitcnt lgkmcnt(6)
	v_mfma_f32_16x16x32_bf16 v[38:41], v[134:137], v[158:161], v[38:41]
	v_mfma_f32_16x16x32_bf16 v[102:105], v[142:145], v[158:161], v[102:105]
	ds_read_b64_tr_b16 v[158:159], v217 offset:51968
	ds_read_b64_tr_b16 v[160:161], v217 offset:60160
	s_waitcnt lgkmcnt(6)
	v_mfma_f32_16x16x32_bf16 v[42:45], v[130:133], v[146:149], v[42:45]
	v_mfma_f32_16x16x32_bf16 v[106:109], v[138:141], v[146:149], v[106:109]
	ds_read_b64_tr_b16 v[146:147], v217 offset:35840
	ds_read_b64_tr_b16 v[148:149], v217 offset:44032
	s_waitcnt lgkmcnt(6)
	v_mfma_f32_16x16x32_bf16 v[42:45], v[134:137], v[150:153], v[42:45]
	v_mfma_f32_16x16x32_bf16 v[106:109], v[142:145], v[150:153], v[106:109]
	ds_read_b64_tr_b16 v[150:151], v217 offset:52224
	ds_read_b64_tr_b16 v[152:153], v217 offset:60416
	s_waitcnt lgkmcnt(6)
	v_mfma_f32_16x16x32_bf16 v[46:49], v[130:133], v[154:157], v[46:49]
	v_mfma_f32_16x16x32_bf16 v[110:113], v[138:141], v[154:157], v[110:113]
	ds_read_b64_tr_b16 v[154:155], v217 offset:36096
	ds_read_b64_tr_b16 v[156:157], v217 offset:44288
	s_waitcnt lgkmcnt(6)
	v_mfma_f32_16x16x32_bf16 v[46:49], v[134:137], v[158:161], v[46:49]
	v_mfma_f32_16x16x32_bf16 v[110:113], v[142:145], v[158:161], v[110:113]
	ds_read_b64_tr_b16 v[158:159], v217 offset:52480
	ds_read_b64_tr_b16 v[160:161], v217 offset:60672
	s_waitcnt lgkmcnt(6)
	v_mfma_f32_16x16x32_bf16 v[50:53], v[130:133], v[146:149], v[50:53]
	v_mfma_f32_16x16x32_bf16 v[114:117], v[138:141], v[146:149], v[114:117]
	ds_read_b64_tr_b16 v[146:147], v217 offset:36352
	ds_read_b64_tr_b16 v[148:149], v217 offset:44544
	s_waitcnt lgkmcnt(6)
	v_mfma_f32_16x16x32_bf16 v[50:53], v[134:137], v[150:153], v[50:53]
	v_mfma_f32_16x16x32_bf16 v[114:117], v[142:145], v[150:153], v[114:117]
	ds_read_b64_tr_b16 v[150:151], v217 offset:52736
	ds_read_b64_tr_b16 v[152:153], v217 offset:60928
	s_waitcnt lgkmcnt(6)
	v_mfma_f32_16x16x32_bf16 v[54:57], v[130:133], v[154:157], v[54:57]
	v_mfma_f32_16x16x32_bf16 v[118:121], v[138:141], v[154:157], v[118:121]
	ds_read_b64_tr_b16 v[154:155], v217 offset:36608
	ds_read_b64_tr_b16 v[156:157], v217 offset:44800
	s_waitcnt lgkmcnt(6)
	v_mfma_f32_16x16x32_bf16 v[54:57], v[134:137], v[158:161], v[54:57]
	v_mfma_f32_16x16x32_bf16 v[118:121], v[142:145], v[158:161], v[118:121]
	ds_read_b64_tr_b16 v[158:159], v217 offset:52992
	ds_read_b64_tr_b16 v[160:161], v217 offset:61184
	s_waitcnt lgkmcnt(6)
	v_mfma_f32_16x16x32_bf16 v[58:61], v[130:133], v[146:149], v[58:61]
	v_mfma_f32_16x16x32_bf16 v[122:125], v[138:141], v[146:149], v[122:125]
	s_waitcnt lgkmcnt(4)
	v_mfma_f32_16x16x32_bf16 v[58:61], v[134:137], v[150:153], v[58:61]
	v_mfma_f32_16x16x32_bf16 v[122:125], v[142:145], v[150:153], v[122:125]
	s_waitcnt lgkmcnt(2)
	v_mfma_f32_16x16x32_bf16 v[62:65], v[130:133], v[154:157], v[62:65]
	v_mfma_f32_16x16x32_bf16 v[126:129], v[138:141], v[154:157], v[126:129]
	s_waitcnt lgkmcnt(0)
	v_mfma_f32_16x16x32_bf16 v[62:65], v[134:137], v[158:161], v[62:65]
	v_mfma_f32_16x16x32_bf16 v[126:129], v[142:145], v[158:161], v[126:129]
	s_branch .Ld16a_end1

.LBB0_803:
	ds_bpermute_b32 v246, v224, v0
	ds_bpermute_b32 v247, v224, v223
	s_waitcnt lgkmcnt(0)
	v_add_f32_e32 v0, v0, v246
	v_add_f32_e32 v223, v223, v247
	v_mov_b32_e32 v246, v0
	v_mov_b32_e32 v247, v223
	s_nop 1
	v_permlane32_swap_b32_e32 v0, v246
	v_permlane32_swap_b32_e32 v223, v247
	v_add_f32_e32 v0, v0, v246
	v_add_f32_e32 v223, v223, v247
	s_nop 1
	s_and_saveexec_b64 s[34:35], s[0:1]
	ds_write_b32 v232, v0
	ds_write_b32 v232, v223 offset:64
	s_or_b64 exec, exec, s[34:35]
	s_waitcnt lgkmcnt(0)
	ds_read_b128 v[146:149], v231
	ds_read_b128 v[150:153], v231 offset:64
	s_lshl_b64 s[2:3], s[2:3], 12
	s_add_u32 s2, s42, s2
	s_addc_u32 s3, s43, s3
	s_lshl_b32 s4, s52, 9
	s_add_u32 s4, s2, s4
	s_addc_u32 s34, s3, 0
	s_lshl_b64 s[2:3], s[30:31], 12
	s_add_u32 s30, s4, s2
	s_addc_u32 s31, s34, s3
	v_mbcnt_lo_u32_b32 v202, -1, 0
	v_mbcnt_hi_u32_b32 v202, -1, v202
	v_and_b32_e32 v203, 15, v202
	v_lshrrev_b32_e32 v204, 4, v202
	v_lshlrev_b32_e32 v204, 14, v204
	v_lshl_or_b32 v204, v203, 1, v204
	v_and_b32_e32 v203, 1, v202
	v_cmp_eq_u32_e64 s[76:77], 0, v203
	s_waitcnt lgkmcnt(0)
	v_rcp_f32_e32 v146, v146
	v_rcp_f32_e32 v147, v147
	v_rcp_f32_e32 v148, v148
	v_rcp_f32_e32 v149, v149
	v_rcp_f32_e32 v150, v150
	v_rcp_f32_e32 v151, v151
	v_rcp_f32_e32 v152, v152
	v_rcp_f32_e32 v153, v153
	s_nop 0
	v_mov_b32_e32 v205, v204
	v_mul_f32_e32 v2, v2, v146
	v_mul_f32_e32 v6, v6, v146
	v_mul_f32_e32 v10, v10, v146
	v_mul_f32_e32 v14, v14, v146
	v_mul_f32_e32 v18, v18, v146
	v_mul_f32_e32 v22, v22, v146
	v_mul_f32_e32 v26, v26, v146
	v_mul_f32_e32 v30, v30, v146
	v_mul_f32_e32 v34, v34, v146
	v_mul_f32_e32 v38, v38, v146
	v_mul_f32_e32 v42, v42, v146
	v_mul_f32_e32 v46, v46, v146
	v_mul_f32_e32 v50, v50, v146
	v_mul_f32_e32 v54, v54, v146
	v_mul_f32_e32 v58, v58, v146
	v_mul_f32_e32 v62, v62, v146
	v_mov_b32_dpp v162, v2 quad_perm:[1,0,3,2] row_mask:0xf bank_mask:0xf
	v_mov_b32_dpp v163, v6 quad_perm:[1,0,3,2] row_mask:0xf bank_mask:0xf
	v_mov_b32_dpp v164, v10 quad_perm:[1,0,3,2] row_mask:0xf bank_mask:0xf
	v_mov_b32_dpp v165, v14 quad_perm:[1,0,3,2] row_mask:0xf bank_mask:0xf
	v_mov_b32_dpp v166, v18 quad_perm:[1,0,3,2] row_mask:0xf bank_mask:0xf
	v_mov_b32_dpp v167, v22 quad_perm:[1,0,3,2] row_mask:0xf bank_mask:0xf
	v_mov_b32_dpp v168, v26 quad_perm:[1,0,3,2] row_mask:0xf bank_mask:0xf
	v_mov_b32_dpp v169, v30 quad_perm:[1,0,3,2] row_mask:0xf bank_mask:0xf
	v_mov_b32_dpp v170, v34 quad_perm:[1,0,3,2] row_mask:0xf bank_mask:0xf
	v_mov_b32_dpp v171, v38 quad_perm:[1,0,3,2] row_mask:0xf bank_mask:0xf
	v_mov_b32_dpp v172, v42 quad_perm:[1,0,3,2] row_mask:0xf bank_mask:0xf
	v_mov_b32_dpp v173, v46 quad_perm:[1,0,3,2] row_mask:0xf bank_mask:0xf
	v_mov_b32_dpp v174, v50 quad_perm:[1,0,3,2] row_mask:0xf bank_mask:0xf
	v_mov_b32_dpp v175, v54 quad_perm:[1,0,3,2] row_mask:0xf bank_mask:0xf
	v_mov_b32_dpp v176, v58 quad_perm:[1,0,3,2] row_mask:0xf bank_mask:0xf
	v_mov_b32_dpp v177, v62 quad_perm:[1,0,3,2] row_mask:0xf bank_mask:0xf
	v_cvt_pk_bf16_f32 v2, v2, v162
	v_cvt_pk_bf16_f32 v6, v6, v163
	v_cvt_pk_bf16_f32 v10, v10, v164
	v_cvt_pk_bf16_f32 v14, v14, v165
	v_cvt_pk_bf16_f32 v18, v18, v166
	v_cvt_pk_bf16_f32 v22, v22, v167
	v_cvt_pk_bf16_f32 v26, v26, v168
	v_cvt_pk_bf16_f32 v30, v30, v169
	v_cvt_pk_bf16_f32 v34, v34, v170
	v_cvt_pk_bf16_f32 v38, v38, v171
	v_cvt_pk_bf16_f32 v42, v42, v172
	v_cvt_pk_bf16_f32 v46, v46, v173
	v_cvt_pk_bf16_f32 v50, v50, v174
	v_cvt_pk_bf16_f32 v54, v54, v175
	v_cvt_pk_bf16_f32 v58, v58, v176
	v_cvt_pk_bf16_f32 v62, v62, v177
	s_mov_b64 exec, s[76:77]
	global_store_dword v205, v2, s[30:31] offset:0
	global_store_dword v205, v6, s[30:31] offset:32
	global_store_dword v205, v10, s[30:31] offset:64
	global_store_dword v205, v14, s[30:31] offset:96
	global_store_dword v205, v18, s[30:31] offset:128
	global_store_dword v205, v22, s[30:31] offset:160
	global_store_dword v205, v26, s[30:31] offset:192
	global_store_dword v205, v30, s[30:31] offset:224
	global_store_dword v205, v34, s[30:31] offset:256
	global_store_dword v205, v38, s[30:31] offset:288
	global_store_dword v205, v42, s[30:31] offset:320
	global_store_dword v205, v46, s[30:31] offset:352
	global_store_dword v205, v50, s[30:31] offset:384
	global_store_dword v205, v54, s[30:31] offset:416
	global_store_dword v205, v58, s[30:31] offset:448
	global_store_dword v205, v62, s[30:31] offset:480
	s_mov_b64 exec, -1
	v_add_u32_e32 v205, 0x1000, v204
	v_mul_f32_e32 v3, v3, v147
	v_mul_f32_e32 v7, v7, v147
	v_mul_f32_e32 v11, v11, v147
	v_mul_f32_e32 v15, v15, v147
	v_mul_f32_e32 v19, v19, v147
	v_mul_f32_e32 v23, v23, v147
	v_mul_f32_e32 v27, v27, v147
	v_mul_f32_e32 v31, v31, v147
	v_mul_f32_e32 v35, v35, v147
	v_mul_f32_e32 v39, v39, v147
	v_mul_f32_e32 v43, v43, v147
	v_mul_f32_e32 v47, v47, v147
	v_mul_f32_e32 v51, v51, v147
	v_mul_f32_e32 v55, v55, v147
	v_mul_f32_e32 v59, v59, v147
	v_mul_f32_e32 v63, v63, v147
	v_mov_b32_dpp v162, v3 quad_perm:[1,0,3,2] row_mask:0xf bank_mask:0xf
	v_mov_b32_dpp v163, v7 quad_perm:[1,0,3,2] row_mask:0xf bank_mask:0xf
	v_mov_b32_dpp v164, v11 quad_perm:[1,0,3,2] row_mask:0xf bank_mask:0xf
	v_mov_b32_dpp v165, v15 quad_perm:[1,0,3,2] row_mask:0xf bank_mask:0xf
	v_mov_b32_dpp v166, v19 quad_perm:[1,0,3,2] row_mask:0xf bank_mask:0xf
	v_mov_b32_dpp v167, v23 quad_perm:[1,0,3,2] row_mask:0xf bank_mask:0xf
	v_mov_b32_dpp v168, v27 quad_perm:[1,0,3,2] row_mask:0xf bank_mask:0xf
	v_mov_b32_dpp v169, v31 quad_perm:[1,0,3,2] row_mask:0xf bank_mask:0xf
	v_mov_b32_dpp v170, v35 quad_perm:[1,0,3,2] row_mask:0xf bank_mask:0xf
	v_mov_b32_dpp v171, v39 quad_perm:[1,0,3,2] row_mask:0xf bank_mask:0xf
	v_mov_b32_dpp v172, v43 quad_perm:[1,0,3,2] row_mask:0xf bank_mask:0xf
	v_mov_b32_dpp v173, v47 quad_perm:[1,0,3,2] row_mask:0xf bank_mask:0xf
	v_mov_b32_dpp v174, v51 quad_perm:[1,0,3,2] row_mask:0xf bank_mask:0xf
	v_mov_b32_dpp v175, v55 quad_perm:[1,0,3,2] row_mask:0xf bank_mask:0xf
	v_mov_b32_dpp v176, v59 quad_perm:[1,0,3,2] row_mask:0xf bank_mask:0xf
	v_mov_b32_dpp v177, v63 quad_perm:[1,0,3,2] row_mask:0xf bank_mask:0xf
	v_cvt_pk_bf16_f32 v3, v3, v162
	v_cvt_pk_bf16_f32 v7, v7, v163
	v_cvt_pk_bf16_f32 v11, v11, v164
	v_cvt_pk_bf16_f32 v15, v15, v165
	v_cvt_pk_bf16_f32 v19, v19, v166
	v_cvt_pk_bf16_f32 v23, v23, v167
	v_cvt_pk_bf16_f32 v27, v27, v168
	v_cvt_pk_bf16_f32 v31, v31, v169
	v_cvt_pk_bf16_f32 v35, v35, v170
	v_cvt_pk_bf16_f32 v39, v39, v171
	v_cvt_pk_bf16_f32 v43, v43, v172
	v_cvt_pk_bf16_f32 v47, v47, v173
	v_cvt_pk_bf16_f32 v51, v51, v174
	v_cvt_pk_bf16_f32 v55, v55, v175
	v_cvt_pk_bf16_f32 v59, v59, v176
	v_cvt_pk_bf16_f32 v63, v63, v177
	s_mov_b64 exec, s[76:77]
	global_store_dword v205, v3, s[30:31] offset:0
	global_store_dword v205, v7, s[30:31] offset:32
	global_store_dword v205, v11, s[30:31] offset:64
	global_store_dword v205, v15, s[30:31] offset:96
	global_store_dword v205, v19, s[30:31] offset:128
	global_store_dword v205, v23, s[30:31] offset:160
	global_store_dword v205, v27, s[30:31] offset:192
	global_store_dword v205, v31, s[30:31] offset:224
	global_store_dword v205, v35, s[30:31] offset:256
	global_store_dword v205, v39, s[30:31] offset:288
	global_store_dword v205, v43, s[30:31] offset:320
	global_store_dword v205, v47, s[30:31] offset:352
	global_store_dword v205, v51, s[30:31] offset:384
	global_store_dword v205, v55, s[30:31] offset:416
	global_store_dword v205, v59, s[30:31] offset:448
	global_store_dword v205, v63, s[30:31] offset:480
	s_mov_b64 exec, -1
	v_add_u32_e32 v205, 0x2000, v204
	v_mul_f32_e32 v4, v4, v148
	v_mul_f32_e32 v8, v8, v148
	v_mul_f32_e32 v12, v12, v148
	v_mul_f32_e32 v16, v16, v148
	v_mul_f32_e32 v20, v20, v148
	v_mul_f32_e32 v24, v24, v148
	v_mul_f32_e32 v28, v28, v148
	v_mul_f32_e32 v32, v32, v148
	v_mul_f32_e32 v36, v36, v148
	v_mul_f32_e32 v40, v40, v148
	v_mul_f32_e32 v44, v44, v148
	v_mul_f32_e32 v48, v48, v148
	v_mul_f32_e32 v52, v52, v148
	v_mul_f32_e32 v56, v56, v148
	v_mul_f32_e32 v60, v60, v148
	v_mul_f32_e32 v64, v64, v148
	v_mov_b32_dpp v162, v4 quad_perm:[1,0,3,2] row_mask:0xf bank_mask:0xf
	v_mov_b32_dpp v163, v8 quad_perm:[1,0,3,2] row_mask:0xf bank_mask:0xf
	v_mov_b32_dpp v164, v12 quad_perm:[1,0,3,2] row_mask:0xf bank_mask:0xf
	v_mov_b32_dpp v165, v16 quad_perm:[1,0,3,2] row_mask:0xf bank_mask:0xf
	v_mov_b32_dpp v166, v20 quad_perm:[1,0,3,2] row_mask:0xf bank_mask:0xf
	v_mov_b32_dpp v167, v24 quad_perm:[1,0,3,2] row_mask:0xf bank_mask:0xf
	v_mov_b32_dpp v168, v28 quad_perm:[1,0,3,2] row_mask:0xf bank_mask:0xf
	v_mov_b32_dpp v169, v32 quad_perm:[1,0,3,2] row_mask:0xf bank_mask:0xf
	v_mov_b32_dpp v170, v36 quad_perm:[1,0,3,2] row_mask:0xf bank_mask:0xf
	v_mov_b32_dpp v171, v40 quad_perm:[1,0,3,2] row_mask:0xf bank_mask:0xf
	v_mov_b32_dpp v172, v44 quad_perm:[1,0,3,2] row_mask:0xf bank_mask:0xf
	v_mov_b32_dpp v173, v48 quad_perm:[1,0,3,2] row_mask:0xf bank_mask:0xf
	v_mov_b32_dpp v174, v52 quad_perm:[1,0,3,2] row_mask:0xf bank_mask:0xf
	v_mov_b32_dpp v175, v56 quad_perm:[1,0,3,2] row_mask:0xf bank_mask:0xf
	v_mov_b32_dpp v176, v60 quad_perm:[1,0,3,2] row_mask:0xf bank_mask:0xf
	v_mov_b32_dpp v177, v64 quad_perm:[1,0,3,2] row_mask:0xf bank_mask:0xf
	v_cvt_pk_bf16_f32 v4, v4, v162
	v_cvt_pk_bf16_f32 v8, v8, v163
	v_cvt_pk_bf16_f32 v12, v12, v164
	v_cvt_pk_bf16_f32 v16, v16, v165
	v_cvt_pk_bf16_f32 v20, v20, v166
	v_cvt_pk_bf16_f32 v24, v24, v167
	v_cvt_pk_bf16_f32 v28, v28, v168
	v_cvt_pk_bf16_f32 v32, v32, v169
	v_cvt_pk_bf16_f32 v36, v36, v170
	v_cvt_pk_bf16_f32 v40, v40, v171
	v_cvt_pk_bf16_f32 v44, v44, v172
	v_cvt_pk_bf16_f32 v48, v48, v173
	v_cvt_pk_bf16_f32 v52, v52, v174
	v_cvt_pk_bf16_f32 v56, v56, v175
	v_cvt_pk_bf16_f32 v60, v60, v176
	v_cvt_pk_bf16_f32 v64, v64, v177
	s_mov_b64 exec, s[76:77]
	global_store_dword v205, v4, s[30:31] offset:0
	global_store_dword v205, v8, s[30:31] offset:32
	global_store_dword v205, v12, s[30:31] offset:64
	global_store_dword v205, v16, s[30:31] offset:96
	global_store_dword v205, v20, s[30:31] offset:128
	global_store_dword v205, v24, s[30:31] offset:160
	global_store_dword v205, v28, s[30:31] offset:192
	global_store_dword v205, v32, s[30:31] offset:224
	global_store_dword v205, v36, s[30:31] offset:256
	global_store_dword v205, v40, s[30:31] offset:288
	global_store_dword v205, v44, s[30:31] offset:320
	global_store_dword v205, v48, s[30:31] offset:352
	global_store_dword v205, v52, s[30:31] offset:384
	global_store_dword v205, v56, s[30:31] offset:416
	global_store_dword v205, v60, s[30:31] offset:448
	global_store_dword v205, v64, s[30:31] offset:480
	s_mov_b64 exec, -1
	v_add_u32_e32 v205, 0x3000, v204
	v_mul_f32_e32 v5, v5, v149
	v_mul_f32_e32 v9, v9, v149
	v_mul_f32_e32 v13, v13, v149
	v_mul_f32_e32 v17, v17, v149
	v_mul_f32_e32 v21, v21, v149
	v_mul_f32_e32 v25, v25, v149
	v_mul_f32_e32 v29, v29, v149
	v_mul_f32_e32 v33, v33, v149
	v_mul_f32_e32 v37, v37, v149
	v_mul_f32_e32 v41, v41, v149
	v_mul_f32_e32 v45, v45, v149
	v_mul_f32_e32 v49, v49, v149
	v_mul_f32_e32 v53, v53, v149
	v_mul_f32_e32 v57, v57, v149
	v_mul_f32_e32 v61, v61, v149
	v_mul_f32_e32 v65, v65, v149
	v_mov_b32_dpp v162, v5 quad_perm:[1,0,3,2] row_mask:0xf bank_mask:0xf
	v_mov_b32_dpp v163, v9 quad_perm:[1,0,3,2] row_mask:0xf bank_mask:0xf
	v_mov_b32_dpp v164, v13 quad_perm:[1,0,3,2] row_mask:0xf bank_mask:0xf
	v_mov_b32_dpp v165, v17 quad_perm:[1,0,3,2] row_mask:0xf bank_mask:0xf
	v_mov_b32_dpp v166, v21 quad_perm:[1,0,3,2] row_mask:0xf bank_mask:0xf
	v_mov_b32_dpp v167, v25 quad_perm:[1,0,3,2] row_mask:0xf bank_mask:0xf
	v_mov_b32_dpp v168, v29 quad_perm:[1,0,3,2] row_mask:0xf bank_mask:0xf
	v_mov_b32_dpp v169, v33 quad_perm:[1,0,3,2] row_mask:0xf bank_mask:0xf
	v_mov_b32_dpp v170, v37 quad_perm:[1,0,3,2] row_mask:0xf bank_mask:0xf
	v_mov_b32_dpp v171, v41 quad_perm:[1,0,3,2] row_mask:0xf bank_mask:0xf
	v_mov_b32_dpp v172, v45 quad_perm:[1,0,3,2] row_mask:0xf bank_mask:0xf
	v_mov_b32_dpp v173, v49 quad_perm:[1,0,3,2] row_mask:0xf bank_mask:0xf
	v_mov_b32_dpp v174, v53 quad_perm:[1,0,3,2] row_mask:0xf bank_mask:0xf
	v_mov_b32_dpp v175, v57 quad_perm:[1,0,3,2] row_mask:0xf bank_mask:0xf
	v_mov_b32_dpp v176, v61 quad_perm:[1,0,3,2] row_mask:0xf bank_mask:0xf
	v_mov_b32_dpp v177, v65 quad_perm:[1,0,3,2] row_mask:0xf bank_mask:0xf
	v_cvt_pk_bf16_f32 v5, v5, v162
	v_cvt_pk_bf16_f32 v9, v9, v163
	v_cvt_pk_bf16_f32 v13, v13, v164
	v_cvt_pk_bf16_f32 v17, v17, v165
	v_cvt_pk_bf16_f32 v21, v21, v166
	v_cvt_pk_bf16_f32 v25, v25, v167
	v_cvt_pk_bf16_f32 v29, v29, v168
	v_cvt_pk_bf16_f32 v33, v33, v169
	v_cvt_pk_bf16_f32 v37, v37, v170
	v_cvt_pk_bf16_f32 v41, v41, v171
	v_cvt_pk_bf16_f32 v45, v45, v172
	v_cvt_pk_bf16_f32 v49, v49, v173
	v_cvt_pk_bf16_f32 v53, v53, v174
	v_cvt_pk_bf16_f32 v57, v57, v175
	v_cvt_pk_bf16_f32 v61, v61, v176
	v_cvt_pk_bf16_f32 v65, v65, v177
	s_mov_b64 exec, s[76:77]
	global_store_dword v205, v5, s[30:31] offset:0
	global_store_dword v205, v9, s[30:31] offset:32
	global_store_dword v205, v13, s[30:31] offset:64
	global_store_dword v205, v17, s[30:31] offset:96
	global_store_dword v205, v21, s[30:31] offset:128
	global_store_dword v205, v25, s[30:31] offset:160
	global_store_dword v205, v29, s[30:31] offset:192
	global_store_dword v205, v33, s[30:31] offset:224
	global_store_dword v205, v37, s[30:31] offset:256
	global_store_dword v205, v41, s[30:31] offset:288
	global_store_dword v205, v45, s[30:31] offset:320
	global_store_dword v205, v49, s[30:31] offset:352
	global_store_dword v205, v53, s[30:31] offset:384
	global_store_dword v205, v57, s[30:31] offset:416
	global_store_dword v205, v61, s[30:31] offset:448
	global_store_dword v205, v65, s[30:31] offset:480
	s_mov_b64 exec, -1
	v_add_u32_e32 v205, 0x10000, v204
	v_mul_f32_e32 v66, v66, v150
	v_mul_f32_e32 v70, v70, v150
	v_mul_f32_e32 v74, v74, v150
	v_mul_f32_e32 v78, v78, v150
	v_mul_f32_e32 v82, v82, v150
	v_mul_f32_e32 v86, v86, v150
	v_mul_f32_e32 v90, v90, v150
	v_mul_f32_e32 v94, v94, v150
	v_mul_f32_e32 v98, v98, v150
	v_mul_f32_e32 v102, v102, v150
	v_mul_f32_e32 v106, v106, v150
	v_mul_f32_e32 v110, v110, v150
	v_mul_f32_e32 v114, v114, v150
	v_mul_f32_e32 v118, v118, v150
	v_mul_f32_e32 v122, v122, v150
	v_mul_f32_e32 v126, v126, v150
	v_mov_b32_dpp v162, v66 quad_perm:[1,0,3,2] row_mask:0xf bank_mask:0xf
	v_mov_b32_dpp v163, v70 quad_perm:[1,0,3,2] row_mask:0xf bank_mask:0xf
	v_mov_b32_dpp v164, v74 quad_perm:[1,0,3,2] row_mask:0xf bank_mask:0xf
	v_mov_b32_dpp v165, v78 quad_perm:[1,0,3,2] row_mask:0xf bank_mask:0xf
	v_mov_b32_dpp v166, v82 quad_perm:[1,0,3,2] row_mask:0xf bank_mask:0xf
	v_mov_b32_dpp v167, v86 quad_perm:[1,0,3,2] row_mask:0xf bank_mask:0xf
	v_mov_b32_dpp v168, v90 quad_perm:[1,0,3,2] row_mask:0xf bank_mask:0xf
	v_mov_b32_dpp v169, v94 quad_perm:[1,0,3,2] row_mask:0xf bank_mask:0xf
	v_mov_b32_dpp v170, v98 quad_perm:[1,0,3,2] row_mask:0xf bank_mask:0xf
	v_mov_b32_dpp v171, v102 quad_perm:[1,0,3,2] row_mask:0xf bank_mask:0xf
	v_mov_b32_dpp v172, v106 quad_perm:[1,0,3,2] row_mask:0xf bank_mask:0xf
	v_mov_b32_dpp v173, v110 quad_perm:[1,0,3,2] row_mask:0xf bank_mask:0xf
	v_mov_b32_dpp v174, v114 quad_perm:[1,0,3,2] row_mask:0xf bank_mask:0xf
	v_mov_b32_dpp v175, v118 quad_perm:[1,0,3,2] row_mask:0xf bank_mask:0xf
	v_mov_b32_dpp v176, v122 quad_perm:[1,0,3,2] row_mask:0xf bank_mask:0xf
	v_mov_b32_dpp v177, v126 quad_perm:[1,0,3,2] row_mask:0xf bank_mask:0xf
	v_cvt_pk_bf16_f32 v66, v66, v162
	v_cvt_pk_bf16_f32 v70, v70, v163
	v_cvt_pk_bf16_f32 v74, v74, v164
	v_cvt_pk_bf16_f32 v78, v78, v165
	v_cvt_pk_bf16_f32 v82, v82, v166
	v_cvt_pk_bf16_f32 v86, v86, v167
	v_cvt_pk_bf16_f32 v90, v90, v168
	v_cvt_pk_bf16_f32 v94, v94, v169
	v_cvt_pk_bf16_f32 v98, v98, v170
	v_cvt_pk_bf16_f32 v102, v102, v171
	v_cvt_pk_bf16_f32 v106, v106, v172
	v_cvt_pk_bf16_f32 v110, v110, v173
	v_cvt_pk_bf16_f32 v114, v114, v174
	v_cvt_pk_bf16_f32 v118, v118, v175
	v_cvt_pk_bf16_f32 v122, v122, v176
	v_cvt_pk_bf16_f32 v126, v126, v177
	s_mov_b64 exec, s[76:77]
	global_store_dword v205, v66, s[30:31] offset:0
	global_store_dword v205, v70, s[30:31] offset:32
	global_store_dword v205, v74, s[30:31] offset:64
	global_store_dword v205, v78, s[30:31] offset:96
	global_store_dword v205, v82, s[30:31] offset:128
	global_store_dword v205, v86, s[30:31] offset:160
	global_store_dword v205, v90, s[30:31] offset:192
	global_store_dword v205, v94, s[30:31] offset:224
	global_store_dword v205, v98, s[30:31] offset:256
	global_store_dword v205, v102, s[30:31] offset:288
	global_store_dword v205, v106, s[30:31] offset:320
	global_store_dword v205, v110, s[30:31] offset:352
	global_store_dword v205, v114, s[30:31] offset:384
	global_store_dword v205, v118, s[30:31] offset:416
	global_store_dword v205, v122, s[30:31] offset:448
	global_store_dword v205, v126, s[30:31] offset:480
	s_mov_b64 exec, -1
	v_add_u32_e32 v205, 0x11000, v204
	v_mul_f32_e32 v67, v67, v151
	v_mul_f32_e32 v71, v71, v151
	v_mul_f32_e32 v75, v75, v151
	v_mul_f32_e32 v79, v79, v151
	v_mul_f32_e32 v83, v83, v151
	v_mul_f32_e32 v87, v87, v151
	v_mul_f32_e32 v91, v91, v151
	v_mul_f32_e32 v95, v95, v151
	v_mul_f32_e32 v99, v99, v151
	v_mul_f32_e32 v103, v103, v151
	v_mul_f32_e32 v107, v107, v151
	v_mul_f32_e32 v111, v111, v151
	v_mul_f32_e32 v115, v115, v151
	v_mul_f32_e32 v119, v119, v151
	v_mul_f32_e32 v123, v123, v151
	v_mul_f32_e32 v127, v127, v151
	v_mov_b32_dpp v162, v67 quad_perm:[1,0,3,2] row_mask:0xf bank_mask:0xf
	v_mov_b32_dpp v163, v71 quad_perm:[1,0,3,2] row_mask:0xf bank_mask:0xf
	v_mov_b32_dpp v164, v75 quad_perm:[1,0,3,2] row_mask:0xf bank_mask:0xf
	v_mov_b32_dpp v165, v79 quad_perm:[1,0,3,2] row_mask:0xf bank_mask:0xf
	v_mov_b32_dpp v166, v83 quad_perm:[1,0,3,2] row_mask:0xf bank_mask:0xf
	v_mov_b32_dpp v167, v87 quad_perm:[1,0,3,2] row_mask:0xf bank_mask:0xf
	v_mov_b32_dpp v168, v91 quad_perm:[1,0,3,2] row_mask:0xf bank_mask:0xf
	v_mov_b32_dpp v169, v95 quad_perm:[1,0,3,2] row_mask:0xf bank_mask:0xf
	v_mov_b32_dpp v170, v99 quad_perm:[1,0,3,2] row_mask:0xf bank_mask:0xf
	v_mov_b32_dpp v171, v103 quad_perm:[1,0,3,2] row_mask:0xf bank_mask:0xf
	v_mov_b32_dpp v172, v107 quad_perm:[1,0,3,2] row_mask:0xf bank_mask:0xf
	v_mov_b32_dpp v173, v111 quad_perm:[1,0,3,2] row_mask:0xf bank_mask:0xf
	v_mov_b32_dpp v174, v115 quad_perm:[1,0,3,2] row_mask:0xf bank_mask:0xf
	v_mov_b32_dpp v175, v119 quad_perm:[1,0,3,2] row_mask:0xf bank_mask:0xf
	v_mov_b32_dpp v176, v123 quad_perm:[1,0,3,2] row_mask:0xf bank_mask:0xf
	v_mov_b32_dpp v177, v127 quad_perm:[1,0,3,2] row_mask:0xf bank_mask:0xf
	v_cvt_pk_bf16_f32 v67, v67, v162
	v_cvt_pk_bf16_f32 v71, v71, v163
	v_cvt_pk_bf16_f32 v75, v75, v164
	v_cvt_pk_bf16_f32 v79, v79, v165
	v_cvt_pk_bf16_f32 v83, v83, v166
	v_cvt_pk_bf16_f32 v87, v87, v167
	v_cvt_pk_bf16_f32 v91, v91, v168
	v_cvt_pk_bf16_f32 v95, v95, v169
	v_cvt_pk_bf16_f32 v99, v99, v170
	v_cvt_pk_bf16_f32 v103, v103, v171
	v_cvt_pk_bf16_f32 v107, v107, v172
	v_cvt_pk_bf16_f32 v111, v111, v173
	v_cvt_pk_bf16_f32 v115, v115, v174
	v_cvt_pk_bf16_f32 v119, v119, v175
	v_cvt_pk_bf16_f32 v123, v123, v176
	v_cvt_pk_bf16_f32 v127, v127, v177
	s_mov_b64 exec, s[76:77]
	global_store_dword v205, v67, s[30:31] offset:0
	global_store_dword v205, v71, s[30:31] offset:32
	global_store_dword v205, v75, s[30:31] offset:64
	global_store_dword v205, v79, s[30:31] offset:96
	global_store_dword v205, v83, s[30:31] offset:128
	global_store_dword v205, v87, s[30:31] offset:160
	global_store_dword v205, v91, s[30:31] offset:192
	global_store_dword v205, v95, s[30:31] offset:224
	global_store_dword v205, v99, s[30:31] offset:256
	global_store_dword v205, v103, s[30:31] offset:288
	global_store_dword v205, v107, s[30:31] offset:320
	global_store_dword v205, v111, s[30:31] offset:352
	global_store_dword v205, v115, s[30:31] offset:384
	global_store_dword v205, v119, s[30:31] offset:416
	global_store_dword v205, v123, s[30:31] offset:448
	global_store_dword v205, v127, s[30:31] offset:480
	s_mov_b64 exec, -1
	v_add_u32_e32 v205, 0x12000, v204
	v_mul_f32_e32 v68, v68, v152
	v_mul_f32_e32 v72, v72, v152
	v_mul_f32_e32 v76, v76, v152
	v_mul_f32_e32 v80, v80, v152
	v_mul_f32_e32 v84, v84, v152
	v_mul_f32_e32 v88, v88, v152
	v_mul_f32_e32 v92, v92, v152
	v_mul_f32_e32 v96, v96, v152
	v_mul_f32_e32 v100, v100, v152
	v_mul_f32_e32 v104, v104, v152
	v_mul_f32_e32 v108, v108, v152
	v_mul_f32_e32 v112, v112, v152
	v_mul_f32_e32 v116, v116, v152
	v_mul_f32_e32 v120, v120, v152
	v_mul_f32_e32 v124, v124, v152
	v_mul_f32_e32 v128, v128, v152
	v_mov_b32_dpp v162, v68 quad_perm:[1,0,3,2] row_mask:0xf bank_mask:0xf
	v_mov_b32_dpp v163, v72 quad_perm:[1,0,3,2] row_mask:0xf bank_mask:0xf
	v_mov_b32_dpp v164, v76 quad_perm:[1,0,3,2] row_mask:0xf bank_mask:0xf
	v_mov_b32_dpp v165, v80 quad_perm:[1,0,3,2] row_mask:0xf bank_mask:0xf
	v_mov_b32_dpp v166, v84 quad_perm:[1,0,3,2] row_mask:0xf bank_mask:0xf
	v_mov_b32_dpp v167, v88 quad_perm:[1,0,3,2] row_mask:0xf bank_mask:0xf
	v_mov_b32_dpp v168, v92 quad_perm:[1,0,3,2] row_mask:0xf bank_mask:0xf
	v_mov_b32_dpp v169, v96 quad_perm:[1,0,3,2] row_mask:0xf bank_mask:0xf
	v_mov_b32_dpp v170, v100 quad_perm:[1,0,3,2] row_mask:0xf bank_mask:0xf
	v_mov_b32_dpp v171, v104 quad_perm:[1,0,3,2] row_mask:0xf bank_mask:0xf
	v_mov_b32_dpp v172, v108 quad_perm:[1,0,3,2] row_mask:0xf bank_mask:0xf
	v_mov_b32_dpp v173, v112 quad_perm:[1,0,3,2] row_mask:0xf bank_mask:0xf
	v_mov_b32_dpp v174, v116 quad_perm:[1,0,3,2] row_mask:0xf bank_mask:0xf
	v_mov_b32_dpp v175, v120 quad_perm:[1,0,3,2] row_mask:0xf bank_mask:0xf
	v_mov_b32_dpp v176, v124 quad_perm:[1,0,3,2] row_mask:0xf bank_mask:0xf
	v_mov_b32_dpp v177, v128 quad_perm:[1,0,3,2] row_mask:0xf bank_mask:0xf
	v_cvt_pk_bf16_f32 v68, v68, v162
	v_cvt_pk_bf16_f32 v72, v72, v163
	v_cvt_pk_bf16_f32 v76, v76, v164
	v_cvt_pk_bf16_f32 v80, v80, v165
	v_cvt_pk_bf16_f32 v84, v84, v166
	v_cvt_pk_bf16_f32 v88, v88, v167
	v_cvt_pk_bf16_f32 v92, v92, v168
	v_cvt_pk_bf16_f32 v96, v96, v169
	v_cvt_pk_bf16_f32 v100, v100, v170
	v_cvt_pk_bf16_f32 v104, v104, v171
	v_cvt_pk_bf16_f32 v108, v108, v172
	v_cvt_pk_bf16_f32 v112, v112, v173
	v_cvt_pk_bf16_f32 v116, v116, v174
	v_cvt_pk_bf16_f32 v120, v120, v175
	v_cvt_pk_bf16_f32 v124, v124, v176
	v_cvt_pk_bf16_f32 v128, v128, v177
	s_mov_b64 exec, s[76:77]
	global_store_dword v205, v68, s[30:31] offset:0
	global_store_dword v205, v72, s[30:31] offset:32
	global_store_dword v205, v76, s[30:31] offset:64
	global_store_dword v205, v80, s[30:31] offset:96
	global_store_dword v205, v84, s[30:31] offset:128
	global_store_dword v205, v88, s[30:31] offset:160
	global_store_dword v205, v92, s[30:31] offset:192
	global_store_dword v205, v96, s[30:31] offset:224
	global_store_dword v205, v100, s[30:31] offset:256
	global_store_dword v205, v104, s[30:31] offset:288
	global_store_dword v205, v108, s[30:31] offset:320
	global_store_dword v205, v112, s[30:31] offset:352
	global_store_dword v205, v116, s[30:31] offset:384
	global_store_dword v205, v120, s[30:31] offset:416
	global_store_dword v205, v124, s[30:31] offset:448
	global_store_dword v205, v128, s[30:31] offset:480
	s_mov_b64 exec, -1
	v_add_u32_e32 v205, 0x13000, v204
	v_mul_f32_e32 v69, v69, v153
	v_mul_f32_e32 v73, v73, v153
	v_mul_f32_e32 v77, v77, v153
	v_mul_f32_e32 v81, v81, v153
	v_mul_f32_e32 v85, v85, v153
	v_mul_f32_e32 v89, v89, v153
	v_mul_f32_e32 v93, v93, v153
	v_mul_f32_e32 v97, v97, v153
	v_mul_f32_e32 v101, v101, v153
	v_mul_f32_e32 v105, v105, v153
	v_mul_f32_e32 v109, v109, v153
	v_mul_f32_e32 v113, v113, v153
	v_mul_f32_e32 v117, v117, v153
	v_mul_f32_e32 v121, v121, v153
	v_mul_f32_e32 v125, v125, v153
	v_mul_f32_e32 v129, v129, v153
	v_mov_b32_dpp v162, v69 quad_perm:[1,0,3,2] row_mask:0xf bank_mask:0xf
	v_mov_b32_dpp v163, v73 quad_perm:[1,0,3,2] row_mask:0xf bank_mask:0xf
	v_mov_b32_dpp v164, v77 quad_perm:[1,0,3,2] row_mask:0xf bank_mask:0xf
	v_mov_b32_dpp v165, v81 quad_perm:[1,0,3,2] row_mask:0xf bank_mask:0xf
	v_mov_b32_dpp v166, v85 quad_perm:[1,0,3,2] row_mask:0xf bank_mask:0xf
	v_mov_b32_dpp v167, v89 quad_perm:[1,0,3,2] row_mask:0xf bank_mask:0xf
	v_mov_b32_dpp v168, v93 quad_perm:[1,0,3,2] row_mask:0xf bank_mask:0xf
	v_mov_b32_dpp v169, v97 quad_perm:[1,0,3,2] row_mask:0xf bank_mask:0xf
	v_mov_b32_dpp v170, v101 quad_perm:[1,0,3,2] row_mask:0xf bank_mask:0xf
	v_mov_b32_dpp v171, v105 quad_perm:[1,0,3,2] row_mask:0xf bank_mask:0xf
	v_mov_b32_dpp v172, v109 quad_perm:[1,0,3,2] row_mask:0xf bank_mask:0xf
	v_mov_b32_dpp v173, v113 quad_perm:[1,0,3,2] row_mask:0xf bank_mask:0xf
	v_mov_b32_dpp v174, v117 quad_perm:[1,0,3,2] row_mask:0xf bank_mask:0xf
	v_mov_b32_dpp v175, v121 quad_perm:[1,0,3,2] row_mask:0xf bank_mask:0xf
	v_mov_b32_dpp v176, v125 quad_perm:[1,0,3,2] row_mask:0xf bank_mask:0xf
	v_mov_b32_dpp v177, v129 quad_perm:[1,0,3,2] row_mask:0xf bank_mask:0xf
	v_cvt_pk_bf16_f32 v69, v69, v162
	v_cvt_pk_bf16_f32 v73, v73, v163
	v_cvt_pk_bf16_f32 v77, v77, v164
	v_cvt_pk_bf16_f32 v81, v81, v165
	v_cvt_pk_bf16_f32 v85, v85, v166
	v_cvt_pk_bf16_f32 v89, v89, v167
	v_cvt_pk_bf16_f32 v93, v93, v168
	v_cvt_pk_bf16_f32 v97, v97, v169
	v_cvt_pk_bf16_f32 v101, v101, v170
	v_cvt_pk_bf16_f32 v105, v105, v171
	v_cvt_pk_bf16_f32 v109, v109, v172
	v_cvt_pk_bf16_f32 v113, v113, v173
	v_cvt_pk_bf16_f32 v117, v117, v174
	v_cvt_pk_bf16_f32 v121, v121, v175
	v_cvt_pk_bf16_f32 v125, v125, v176
	v_cvt_pk_bf16_f32 v129, v129, v177
	s_mov_b64 exec, s[76:77]
	global_store_dword v205, v69, s[30:31] offset:0
	global_store_dword v205, v73, s[30:31] offset:32
	global_store_dword v205, v77, s[30:31] offset:64
	global_store_dword v205, v81, s[30:31] offset:96
	global_store_dword v205, v85, s[30:31] offset:128
	global_store_dword v205, v89, s[30:31] offset:160
	global_store_dword v205, v93, s[30:31] offset:192
	global_store_dword v205, v97, s[30:31] offset:224
	global_store_dword v205, v101, s[30:31] offset:256
	global_store_dword v205, v105, s[30:31] offset:288
	global_store_dword v205, v109, s[30:31] offset:320
	global_store_dword v205, v113, s[30:31] offset:352
	global_store_dword v205, v117, s[30:31] offset:384
	global_store_dword v205, v121, s[30:31] offset:416
	global_store_dword v205, v125, s[30:31] offset:448
	global_store_dword v205, v129, s[30:31] offset:480
	s_mov_b64 exec, -1
	s_mov_b64 s[30:31], -1
	s_branch .LBB0_784

.LBB0_2410:
	s_sub_i32 s73, s60, 158
	s_cmp_gt_i32 s73, s4
	s_cbranch_scc1 .Ld16c_end0
	ds_read_b128 v[238:241], v218 offset:0
	ds_read_b128 v[242:245], v219 offset:0
	ds_read_b128 v[246:249], v218 offset:128
	s_waitcnt lgkmcnt(2)
	v_mfma_f32_16x16x32_bf16 v[130:133], v[238:241], v[162:165], 0
	v_mfma_f32_16x16x32_bf16 v[146:149], v[238:241], v[178:181], 0
	ds_read_b128 v[238:241], v219 offset:128
	s_waitcnt lgkmcnt(2)
	v_mfma_f32_16x16x32_bf16 v[130:133], v[242:245], v[166:169], v[130:133]
	v_mfma_f32_16x16x32_bf16 v[146:149], v[242:245], v[182:185], v[146:149]
	ds_read_b128 v[242:245], v218 offset:4096
	s_waitcnt lgkmcnt(2)
	v_mfma_f32_16x16x32_bf16 v[130:133], v[246:249], v[170:173], v[130:133]
	v_mfma_f32_16x16x32_bf16 v[146:149], v[246:249], v[186:189], v[146:149]
	ds_read_b128 v[246:249], v219 offset:4096
	s_waitcnt lgkmcnt(2)
	v_mfma_f32_16x16x32_bf16 v[130:133], v[238:241], v[174:177], v[130:133]
	v_mfma_f32_16x16x32_bf16 v[146:149], v[238:241], v[190:193], v[146:149]
	ds_read_b128 v[238:241], v218 offset:4224
	s_waitcnt lgkmcnt(2)
	v_mfma_f32_16x16x32_bf16 v[134:137], v[242:245], v[162:165], 0
	v_mfma_f32_16x16x32_bf16 v[150:153], v[242:245], v[178:181], 0
	ds_read_b128 v[242:245], v219 offset:4224
	s_waitcnt lgkmcnt(2)
	v_mfma_f32_16x16x32_bf16 v[134:137], v[246:249], v[166:169], v[134:137]
	v_mfma_f32_16x16x32_bf16 v[150:153], v[246:249], v[182:185], v[150:153]
	ds_read_b128 v[246:249], v218 offset:8192
	s_waitcnt lgkmcnt(2)
	v_mfma_f32_16x16x32_bf16 v[134:137], v[238:241], v[170:173], v[134:137]
	v_mfma_f32_16x16x32_bf16 v[150:153], v[238:241], v[186:189], v[150:153]
	ds_read_b128 v[238:241], v219 offset:8192
	s_waitcnt lgkmcnt(2)
	v_mfma_f32_16x16x32_bf16 v[134:137], v[242:245], v[174:177], v[134:137]
	v_mfma_f32_16x16x32_bf16 v[150:153], v[242:245], v[190:193], v[150:153]
	ds_read_b128 v[242:245], v218 offset:8320
	s_waitcnt lgkmcnt(2)
	v_mfma_f32_16x16x32_bf16 v[138:141], v[246:249], v[162:165], 0
	v_mfma_f32_16x16x32_bf16 v[154:157], v[246:249], v[178:181], 0
	ds_read_b128 v[246:249], v219 offset:8320
	s_waitcnt lgkmcnt(2)
	v_mfma_f32_16x16x32_bf16 v[138:141], v[238:241], v[166:169], v[138:141]
	v_mfma_f32_16x16x32_bf16 v[154:157], v[238:241], v[182:185], v[154:157]
	ds_read_b128 v[238:241], v218 offset:12288
	s_waitcnt lgkmcnt(2)
	v_mfma_f32_16x16x32_bf16 v[138:141], v[242:245], v[170:173], v[138:141]
	v_mfma_f32_16x16x32_bf16 v[154:157], v[242:245], v[186:189], v[154:157]
	ds_read_b128 v[242:245], v219 offset:12288
	s_waitcnt lgkmcnt(2)
	v_mfma_f32_16x16x32_bf16 v[138:141], v[246:249], v[174:177], v[138:141]
	v_mfma_f32_16x16x32_bf16 v[154:157], v[246:249], v[190:193], v[154:157]
	ds_read_b128 v[246:249], v218 offset:12416
	s_waitcnt lgkmcnt(2)
	v_mfma_f32_16x16x32_bf16 v[142:145], v[238:241], v[162:165], 0
	v_mfma_f32_16x16x32_bf16 v[158:161], v[238:241], v[178:181], 0
	ds_read_b128 v[238:241], v219 offset:12416
	s_waitcnt lgkmcnt(2)
	v_mfma_f32_16x16x32_bf16 v[142:145], v[242:245], v[166:169], v[142:145]
	v_mfma_f32_16x16x32_bf16 v[158:161], v[242:245], v[182:185], v[158:161]
	s_waitcnt lgkmcnt(1)
	v_mfma_f32_16x16x32_bf16 v[142:145], v[246:249], v[170:173], v[142:145]
	v_mfma_f32_16x16x32_bf16 v[158:161], v[246:249], v[186:189], v[158:161]
	s_waitcnt lgkmcnt(0)
	v_mfma_f32_16x16x32_bf16 v[142:145], v[238:241], v[174:177], v[142:145]
	v_mfma_f32_16x16x32_bf16 v[158:161], v[238:241], v[190:193], v[158:161]
	s_nop 7
	s_nop 1
	s_sub_i32 s40, s60, 64
	s_cmp_le_i32 s40, s4
	s_cbranch_scc1 .Ld16c_nm0
	v_cmp_gt_i32_e64 s[74:75], 0, v233
	v_cmp_gt_i32_e64 s[76:77], 1, v233
	v_cmp_gt_i32_e64 s[78:79], 2, v233
	v_cmp_gt_i32_e64 s[80:81], 3, v233
	v_cndmask_b32_e64 v130, v130, v230, s[74:75]
	v_cndmask_b32_e64 v131, v131, v230, s[76:77]
	v_cndmask_b32_e64 v132, v132, v230, s[78:79]
	v_cndmask_b32_e64 v133, v133, v230, s[80:81]
	v_cmp_gt_i32_e64 s[74:75], 16, v233
	v_cmp_gt_i32_e64 s[76:77], 17, v233
	v_cmp_gt_i32_e64 s[78:79], 18, v233
	v_cmp_gt_i32_e64 s[80:81], 19, v233
	v_cndmask_b32_e64 v134, v134, v230, s[74:75]
	v_cndmask_b32_e64 v135, v135, v230, s[76:77]
	v_cndmask_b32_e64 v136, v136, v230, s[78:79]
	v_cndmask_b32_e64 v137, v137, v230, s[80:81]
	v_cmp_gt_i32_e64 s[74:75], 32, v233
	v_cmp_gt_i32_e64 s[76:77], 33, v233
	v_cmp_gt_i32_e64 s[78:79], 34, v233
	v_cmp_gt_i32_e64 s[80:81], 35, v233
	v_cndmask_b32_e64 v138, v138, v230, s[74:75]
	v_cndmask_b32_e64 v139, v139, v230, s[76:77]
	v_cndmask_b32_e64 v140, v140, v230, s[78:79]
	v_cndmask_b32_e64 v141, v141, v230, s[80:81]
	v_cmp_gt_i32_e64 s[74:75], 48, v233
	v_cmp_gt_i32_e64 s[76:77], 49, v233
	v_cmp_gt_i32_e64 s[78:79], 50, v233
	v_cmp_gt_i32_e64 s[80:81], 51, v233
	v_cndmask_b32_e64 v142, v142, v230, s[74:75]
	v_cndmask_b32_e64 v143, v143, v230, s[76:77]
	v_cndmask_b32_e64 v144, v144, v230, s[78:79]
	v_cndmask_b32_e64 v145, v145, v230, s[80:81]
	v_cmp_gt_i32_e64 s[74:75], -16, v233
	v_cmp_gt_i32_e64 s[76:77], -15, v233
	v_cmp_gt_i32_e64 s[78:79], -14, v233
	v_cmp_gt_i32_e64 s[80:81], -13, v233
	v_cndmask_b32_e64 v146, v146, v230, s[74:75]
	v_cndmask_b32_e64 v147, v147, v230, s[76:77]
	v_cndmask_b32_e64 v148, v148, v230, s[78:79]
	v_cndmask_b32_e64 v149, v149, v230, s[80:81]
	v_cmp_gt_i32_e64 s[74:75], 0, v233
	v_cmp_gt_i32_e64 s[76:77], 1, v233
	v_cmp_gt_i32_e64 s[78:79], 2, v233
	v_cmp_gt_i32_e64 s[80:81], 3, v233
	v_cndmask_b32_e64 v150, v150, v230, s[74:75]
	v_cndmask_b32_e64 v151, v151, v230, s[76:77]
	v_cndmask_b32_e64 v152, v152, v230, s[78:79]
	v_cndmask_b32_e64 v153, v153, v230, s[80:81]
	v_cmp_gt_i32_e64 s[74:75], 16, v233
	v_cmp_gt_i32_e64 s[76:77], 17, v233
	v_cmp_gt_i32_e64 s[78:79], 18, v233
	v_cmp_gt_i32_e64 s[80:81], 19, v233
	v_cndmask_b32_e64 v154, v154, v230, s[74:75]
	v_cndmask_b32_e64 v155, v155, v230, s[76:77]
	v_cndmask_b32_e64 v156, v156, v230, s[78:79]
	v_cndmask_b32_e64 v157, v157, v230, s[80:81]
	v_cmp_gt_i32_e64 s[74:75], 32, v233
	v_cmp_gt_i32_e64 s[76:77], 33, v233
	v_cmp_gt_i32_e64 s[78:79], 34, v233
	v_cmp_gt_i32_e64 s[80:81], 35, v233
	v_cndmask_b32_e64 v158, v158, v230, s[74:75]
	v_cndmask_b32_e64 v159, v159, v230, s[76:77]
	v_cndmask_b32_e64 v160, v160, v230, s[78:79]
	v_cndmask_b32_e64 v161, v161, v230, s[80:81]
.Ld16c_nm0:
	v_max3_f32 v234, v130, v131, v132
	v_max3_f32 v234, v234, v133, v134
	v_max3_f32 v234, v234, v135, v136
	v_max3_f32 v234, v234, v137, v138
	v_max3_f32 v234, v234, v139, v140
	v_max3_f32 v234, v234, v141, v142
	v_max3_f32 v234, v234, v143, v144
	v_max_f32_e32 v234, v234, v145
	v_max3_f32 v235, v146, v147, v148
	v_max3_f32 v235, v235, v149, v150
	v_max3_f32 v235, v235, v151, v152
	v_max3_f32 v235, v235, v153, v154
	v_max3_f32 v235, v235, v155, v156
	v_max3_f32 v235, v235, v157, v158
	v_max3_f32 v235, v235, v159, v160
	v_max_f32_e32 v235, v235, v161
	ds_bpermute_b32 v246, v224, v234
	ds_bpermute_b32 v247, v224, v235
	s_waitcnt lgkmcnt(0)
	v_max_f32_e32 v234, v234, v246
	v_max_f32_e32 v235, v235, v247
	v_mov_b32_e32 v246, v234
	v_mov_b32_e32 v247, v235
	s_nop 1
	v_permlane32_swap_b32_e32 v234, v246
	v_permlane32_swap_b32_e32 v235, v247
	v_max_f32_e32 v234, v234, v246
	v_max_f32_e32 v235, v235, v247
	v_sub_f32_e32 v246, v234, v237
	v_sub_f32_e32 v247, v235, v222
	v_max_f32_e32 v246, v246, v247
	v_mul_f32_e32 v246, 0x3db504f3, v246
	v_cmp_ge_f32_e32 vcc, s54, v246
	s_nop 3
	s_cmp_eq_u64 vcc, exec
	s_cbranch_scc0 .Ld16c_sl0

.Ld16c_end0:
	s_waitcnt vmcnt(0)
	s_cmp_gt_u32 s61, s59
	s_cselect_b64 s[40:41], -1, 0
	s_and_b64 vcc, exec, s[40:41]
	s_waitcnt vmcnt(0) lgkmcnt(0)
	s_barrier
	s_cbranch_vccnz .LBB0_2418
	s_mov_b64 s[42:43], src_shared_base
	s_cmp_lg_u32 0, -1
	s_cselect_b32 s42, 0, 0
	s_cselect_b32 s43, s43, 0
	s_add_u32 s42, s42, 0x10000
	s_addc_u32 s43, s43, 0
	s_cmp_lg_u64 s[42:43], 0
	s_cselect_b32 s42, s42, -1
	s_add_i32 s42, s42, s57
	v_lshl_add_u64 v[130:131], v[206:207], 0, s[24:25]
	s_mov_b32 m0, s42
	s_nop 0
	global_load_lds_dwordx4 v[130:131], off
	v_lshl_add_u64 v[130:131], v[204:205], 0, s[24:25]
	s_add_i32 m0, s42, 0x400
	s_add_i32 s42, s58, 0
	global_load_lds_dwordx4 v[130:131], off
	v_lshl_add_u64 v[130:131], v[202:203], 0, s[26:27]
	s_mov_b32 m0, s42
	s_nop 0
	global_load_lds_dwordx4 v[130:131], off
	v_lshl_add_u64 v[130:131], v[202:203], 0, s[28:29]
	s_add_i32 m0, s42, 0x400
	s_nop 0
	global_load_lds_dwordx4 v[130:131], off
	v_lshl_add_u64 v[130:131], v[202:203], 0, s[30:31]
	s_add_i32 m0, s42, 0x800
	s_nop 0
	global_load_lds_dwordx4 v[130:131], off
	v_lshl_add_u64 v[130:131], v[202:203], 0, s[34:35]
	s_add_i32 m0, s42, 0xc00
	s_nop 0
	global_load_lds_dwordx4 v[130:131], off
.LBB0_2418:
	s_sub_i32 s73, s60, 94
	s_cmp_gt_i32 s73, s4
	s_cbranch_scc1 .Ld16c_end1
	ds_read_b128 v[238:241], v218 offset:16384
	ds_read_b128 v[242:245], v219 offset:16384
	ds_read_b128 v[246:249], v218 offset:16512
	s_waitcnt lgkmcnt(2)
	v_mfma_f32_16x16x32_bf16 v[130:133], v[238:241], v[162:165], 0
	v_mfma_f32_16x16x32_bf16 v[146:149], v[238:241], v[178:181], 0
	ds_read_b128 v[238:241], v219 offset:16512
	s_waitcnt lgkmcnt(2)
	v_mfma_f32_16x16x32_bf16 v[130:133], v[242:245], v[166:169], v[130:133]
	v_mfma_f32_16x16x32_bf16 v[146:149], v[242:245], v[182:185], v[146:149]
	ds_read_b128 v[242:245], v218 offset:20480
	s_waitcnt lgkmcnt(2)
	v_mfma_f32_16x16x32_bf16 v[130:133], v[246:249], v[170:173], v[130:133]
	v_mfma_f32_16x16x32_bf16 v[146:149], v[246:249], v[186:189], v[146:149]
	ds_read_b128 v[246:249], v219 offset:20480
	s_waitcnt lgkmcnt(2)
	v_mfma_f32_16x16x32_bf16 v[130:133], v[238:241], v[174:177], v[130:133]
	v_mfma_f32_16x16x32_bf16 v[146:149], v[238:241], v[190:193], v[146:149]
	ds_read_b128 v[238:241], v218 offset:20608
	s_waitcnt lgkmcnt(2)
	v_mfma_f32_16x16x32_bf16 v[134:137], v[242:245], v[162:165], 0
	v_mfma_f32_16x16x32_bf16 v[150:153], v[242:245], v[178:181], 0
	ds_read_b128 v[242:245], v219 offset:20608
	s_waitcnt lgkmcnt(2)
	v_mfma_f32_16x16x32_bf16 v[134:137], v[246:249], v[166:169], v[134:137]
	v_mfma_f32_16x16x32_bf16 v[150:153], v[246:249], v[182:185], v[150:153]
	ds_read_b128 v[246:249], v218 offset:24576
	s_waitcnt lgkmcnt(2)
	v_mfma_f32_16x16x32_bf16 v[134:137], v[238:241], v[170:173], v[134:137]
	v_mfma_f32_16x16x32_bf16 v[150:153], v[238:241], v[186:189], v[150:153]
	ds_read_b128 v[238:241], v219 offset:24576
	s_waitcnt lgkmcnt(2)
	v_mfma_f32_16x16x32_bf16 v[134:137], v[242:245], v[174:177], v[134:137]
	v_mfma_f32_16x16x32_bf16 v[150:153], v[242:245], v[190:193], v[150:153]
	ds_read_b128 v[242:245], v218 offset:24704
	s_waitcnt lgkmcnt(2)
	v_mfma_f32_16x16x32_bf16 v[138:141], v[246:249], v[162:165], 0
	v_mfma_f32_16x16x32_bf16 v[154:157], v[246:249], v[178:181], 0
	ds_read_b128 v[246:249], v219 offset:24704
	s_waitcnt lgkmcnt(2)
	v_mfma_f32_16x16x32_bf16 v[138:141], v[238:241], v[166:169], v[138:141]
	v_mfma_f32_16x16x32_bf16 v[154:157], v[238:241], v[182:185], v[154:157]
	ds_read_b128 v[238:241], v218 offset:28672
	s_waitcnt lgkmcnt(2)
	v_mfma_f32_16x16x32_bf16 v[138:141], v[242:245], v[170:173], v[138:141]
	v_mfma_f32_16x16x32_bf16 v[154:157], v[242:245], v[186:189], v[154:157]
	ds_read_b128 v[242:245], v219 offset:28672
	s_waitcnt lgkmcnt(2)
	v_mfma_f32_16x16x32_bf16 v[138:141], v[246:249], v[174:177], v[138:141]
	v_mfma_f32_16x16x32_bf16 v[154:157], v[246:249], v[190:193], v[154:157]
	ds_read_b128 v[246:249], v218 offset:28800
	s_waitcnt lgkmcnt(2)
	v_mfma_f32_16x16x32_bf16 v[142:145], v[238:241], v[162:165], 0
	v_mfma_f32_16x16x32_bf16 v[158:161], v[238:241], v[178:181], 0
	ds_read_b128 v[238:241], v219 offset:28800
	s_waitcnt lgkmcnt(2)
	v_mfma_f32_16x16x32_bf16 v[142:145], v[242:245], v[166:169], v[142:145]
	v_mfma_f32_16x16x32_bf16 v[158:161], v[242:245], v[182:185], v[158:161]
	s_waitcnt lgkmcnt(1)
	v_mfma_f32_16x16x32_bf16 v[142:145], v[246:249], v[170:173], v[142:145]
	v_mfma_f32_16x16x32_bf16 v[158:161], v[246:249], v[186:189], v[158:161]
	s_waitcnt lgkmcnt(0)
	v_mfma_f32_16x16x32_bf16 v[142:145], v[238:241], v[174:177], v[142:145]
	v_mfma_f32_16x16x32_bf16 v[158:161], v[238:241], v[190:193], v[158:161]
	s_nop 7
	s_nop 1
	s_cmp_le_i32 s60, s4
	s_cbranch_scc1 .Ld16c_nm1
	v_subrev_u32_e32 v246, 64, v233
	v_cmp_gt_i32_e64 s[74:75], 0, v246
	v_cmp_gt_i32_e64 s[76:77], 1, v246
	v_cmp_gt_i32_e64 s[78:79], 2, v246
	v_cmp_gt_i32_e64 s[80:81], 3, v246
	v_cndmask_b32_e64 v130, v130, v230, s[74:75]
	v_cndmask_b32_e64 v131, v131, v230, s[76:77]
	v_cndmask_b32_e64 v132, v132, v230, s[78:79]
	v_cndmask_b32_e64 v133, v133, v230, s[80:81]
	v_cmp_gt_i32_e64 s[74:75], 16, v246
	v_cmp_gt_i32_e64 s[76:77], 17, v246
	v_cmp_gt_i32_e64 s[78:79], 18, v246
	v_cmp_gt_i32_e64 s[80:81], 19, v246
	v_cndmask_b32_e64 v134, v134, v230, s[74:75]
	v_cndmask_b32_e64 v135, v135, v230, s[76:77]
	v_cndmask_b32_e64 v136, v136, v230, s[78:79]
	v_cndmask_b32_e64 v137, v137, v230, s[80:81]
	v_cmp_gt_i32_e64 s[74:75], 32, v246
	v_cmp_gt_i32_e64 s[76:77], 33, v246
	v_cmp_gt_i32_e64 s[78:79], 34, v246
	v_cmp_gt_i32_e64 s[80:81], 35, v246
	v_cndmask_b32_e64 v138, v138, v230, s[74:75]
	v_cndmask_b32_e64 v139, v139, v230, s[76:77]
	v_cndmask_b32_e64 v140, v140, v230, s[78:79]
	v_cndmask_b32_e64 v141, v141, v230, s[80:81]
	v_cmp_gt_i32_e64 s[74:75], 48, v246
	v_cmp_gt_i32_e64 s[76:77], 49, v246
	v_cmp_gt_i32_e64 s[78:79], 50, v246
	v_cmp_gt_i32_e64 s[80:81], 51, v246
	v_cndmask_b32_e64 v142, v142, v230, s[74:75]
	v_cndmask_b32_e64 v143, v143, v230, s[76:77]
	v_cndmask_b32_e64 v144, v144, v230, s[78:79]
	v_cndmask_b32_e64 v145, v145, v230, s[80:81]
	v_cmp_gt_i32_e64 s[74:75], -16, v246
	v_cmp_gt_i32_e64 s[76:77], -15, v246
	v_cmp_gt_i32_e64 s[78:79], -14, v246
	v_cmp_gt_i32_e64 s[80:81], -13, v246
	v_cndmask_b32_e64 v146, v146, v230, s[74:75]
	v_cndmask_b32_e64 v147, v147, v230, s[76:77]
	v_cndmask_b32_e64 v148, v148, v230, s[78:79]
	v_cndmask_b32_e64 v149, v149, v230, s[80:81]
	v_cmp_gt_i32_e64 s[74:75], 0, v246
	v_cmp_gt_i32_e64 s[76:77], 1, v246
	v_cmp_gt_i32_e64 s[78:79], 2, v246
	v_cmp_gt_i32_e64 s[80:81], 3, v246
	v_cndmask_b32_e64 v150, v150, v230, s[74:75]
	v_cndmask_b32_e64 v151, v151, v230, s[76:77]
	v_cndmask_b32_e64 v152, v152, v230, s[78:79]
	v_cndmask_b32_e64 v153, v153, v230, s[80:81]
	v_cmp_gt_i32_e64 s[74:75], 16, v246
	v_cmp_gt_i32_e64 s[76:77], 17, v246
	v_cmp_gt_i32_e64 s[78:79], 18, v246
	v_cmp_gt_i32_e64 s[80:81], 19, v246
	v_cndmask_b32_e64 v154, v154, v230, s[74:75]
	v_cndmask_b32_e64 v155, v155, v230, s[76:77]
	v_cndmask_b32_e64 v156, v156, v230, s[78:79]
	v_cndmask_b32_e64 v157, v157, v230, s[80:81]
	v_cmp_gt_i32_e64 s[74:75], 32, v246
	v_cmp_gt_i32_e64 s[76:77], 33, v246
	v_cmp_gt_i32_e64 s[78:79], 34, v246
	v_cmp_gt_i32_e64 s[80:81], 35, v246
	v_cndmask_b32_e64 v158, v158, v230, s[74:75]
	v_cndmask_b32_e64 v159, v159, v230, s[76:77]
	v_cndmask_b32_e64 v160, v160, v230, s[78:79]
	v_cndmask_b32_e64 v161, v161, v230, s[80:81]

.LBB0_2423:
	ds_bpermute_b32 v246, v224, v0
	ds_bpermute_b32 v247, v224, v223
	s_waitcnt lgkmcnt(0)
	v_add_f32_e32 v0, v0, v246
	v_add_f32_e32 v223, v223, v247
	v_mov_b32_e32 v246, v0
	v_mov_b32_e32 v247, v223
	s_nop 1
	v_permlane32_swap_b32_e32 v0, v246
	v_permlane32_swap_b32_e32 v223, v247
	v_add_f32_e32 v0, v0, v246
	v_add_f32_e32 v223, v223, v247
	s_nop 1
	s_and_saveexec_b64 s[38:39], s[0:1]
	ds_write_b32 v232, v0
	ds_write_b32 v232, v223 offset:64
	s_or_b64 exec, exec, s[38:39]
	s_waitcnt lgkmcnt(0)
	ds_read_b128 v[146:149], v231
	ds_read_b128 v[150:153], v231 offset:64
	s_lshl_b64 s[2:3], s[2:3], 12
	s_add_u32 s2, s46, s2
	s_addc_u32 s3, s47, s3
	s_lshl_b32 s4, s56, 9
	s_add_u32 s4, s2, s4
	s_addc_u32 s38, s3, 0
	s_lshl_b64 s[2:3], s[36:37], 12
	s_add_u32 s36, s4, s2
	s_addc_u32 s37, s38, s3
	v_mbcnt_lo_u32_b32 v202, -1, 0
	v_mbcnt_hi_u32_b32 v202, -1, v202
	v_and_b32_e32 v203, 15, v202
	v_lshrrev_b32_e32 v204, 4, v202
	v_lshlrev_b32_e32 v204, 14, v204
	v_lshl_or_b32 v204, v203, 1, v204
	v_and_b32_e32 v203, 1, v202
	v_cmp_eq_u32_e64 s[76:77], 0, v203
	s_waitcnt lgkmcnt(0)
	v_rcp_f32_e32 v146, v146
	v_rcp_f32_e32 v147, v147
	v_rcp_f32_e32 v148, v148
	v_rcp_f32_e32 v149, v149
	v_rcp_f32_e32 v150, v150
	v_rcp_f32_e32 v151, v151
	v_rcp_f32_e32 v152, v152
	v_rcp_f32_e32 v153, v153
	s_nop 0
	v_mov_b32_e32 v205, v204
	v_mul_f32_e32 v2, v2, v146
	v_mul_f32_e32 v6, v6, v146
	v_mul_f32_e32 v10, v10, v146
	v_mul_f32_e32 v14, v14, v146
	v_mul_f32_e32 v18, v18, v146
	v_mul_f32_e32 v22, v22, v146
	v_mul_f32_e32 v26, v26, v146
	v_mul_f32_e32 v30, v30, v146
	v_mul_f32_e32 v34, v34, v146
	v_mul_f32_e32 v38, v38, v146
	v_mul_f32_e32 v42, v42, v146
	v_mul_f32_e32 v46, v46, v146
	v_mul_f32_e32 v50, v50, v146
	v_mul_f32_e32 v54, v54, v146
	v_mul_f32_e32 v58, v58, v146
	v_mul_f32_e32 v62, v62, v146
	v_mov_b32_dpp v162, v2 quad_perm:[1,0,3,2] row_mask:0xf bank_mask:0xf
	v_mov_b32_dpp v163, v6 quad_perm:[1,0,3,2] row_mask:0xf bank_mask:0xf
	v_mov_b32_dpp v164, v10 quad_perm:[1,0,3,2] row_mask:0xf bank_mask:0xf
	v_mov_b32_dpp v165, v14 quad_perm:[1,0,3,2] row_mask:0xf bank_mask:0xf
	v_mov_b32_dpp v166, v18 quad_perm:[1,0,3,2] row_mask:0xf bank_mask:0xf
	v_mov_b32_dpp v167, v22 quad_perm:[1,0,3,2] row_mask:0xf bank_mask:0xf
	v_mov_b32_dpp v168, v26 quad_perm:[1,0,3,2] row_mask:0xf bank_mask:0xf
	v_mov_b32_dpp v169, v30 quad_perm:[1,0,3,2] row_mask:0xf bank_mask:0xf
	v_mov_b32_dpp v170, v34 quad_perm:[1,0,3,2] row_mask:0xf bank_mask:0xf
	v_mov_b32_dpp v171, v38 quad_perm:[1,0,3,2] row_mask:0xf bank_mask:0xf
	v_mov_b32_dpp v172, v42 quad_perm:[1,0,3,2] row_mask:0xf bank_mask:0xf
	v_mov_b32_dpp v173, v46 quad_perm:[1,0,3,2] row_mask:0xf bank_mask:0xf
	v_mov_b32_dpp v174, v50 quad_perm:[1,0,3,2] row_mask:0xf bank_mask:0xf
	v_mov_b32_dpp v175, v54 quad_perm:[1,0,3,2] row_mask:0xf bank_mask:0xf
	v_mov_b32_dpp v176, v58 quad_perm:[1,0,3,2] row_mask:0xf bank_mask:0xf
	v_mov_b32_dpp v177, v62 quad_perm:[1,0,3,2] row_mask:0xf bank_mask:0xf
	v_cvt_pk_bf16_f32 v2, v2, v162
	v_cvt_pk_bf16_f32 v6, v6, v163
	v_cvt_pk_bf16_f32 v10, v10, v164
	v_cvt_pk_bf16_f32 v14, v14, v165
	v_cvt_pk_bf16_f32 v18, v18, v166
	v_cvt_pk_bf16_f32 v22, v22, v167
	v_cvt_pk_bf16_f32 v26, v26, v168
	v_cvt_pk_bf16_f32 v30, v30, v169
	v_cvt_pk_bf16_f32 v34, v34, v170
	v_cvt_pk_bf16_f32 v38, v38, v171
	v_cvt_pk_bf16_f32 v42, v42, v172
	v_cvt_pk_bf16_f32 v46, v46, v173
	v_cvt_pk_bf16_f32 v50, v50, v174
	v_cvt_pk_bf16_f32 v54, v54, v175
	v_cvt_pk_bf16_f32 v58, v58, v176
	v_cvt_pk_bf16_f32 v62, v62, v177
	s_mov_b64 exec, s[76:77]
	global_store_dword v205, v2, s[36:37] offset:0
	global_store_dword v205, v6, s[36:37] offset:32
	global_store_dword v205, v10, s[36:37] offset:64
	global_store_dword v205, v14, s[36:37] offset:96
	global_store_dword v205, v18, s[36:37] offset:128
	global_store_dword v205, v22, s[36:37] offset:160
	global_store_dword v205, v26, s[36:37] offset:192
	global_store_dword v205, v30, s[36:37] offset:224
	global_store_dword v205, v34, s[36:37] offset:256
	global_store_dword v205, v38, s[36:37] offset:288
	global_store_dword v205, v42, s[36:37] offset:320
	global_store_dword v205, v46, s[36:37] offset:352
	global_store_dword v205, v50, s[36:37] offset:384
	global_store_dword v205, v54, s[36:37] offset:416
	global_store_dword v205, v58, s[36:37] offset:448
	global_store_dword v205, v62, s[36:37] offset:480
	s_mov_b64 exec, -1
	v_add_u32_e32 v205, 0x1000, v204
	v_mul_f32_e32 v3, v3, v147
	v_mul_f32_e32 v7, v7, v147
	v_mul_f32_e32 v11, v11, v147
	v_mul_f32_e32 v15, v15, v147
	v_mul_f32_e32 v19, v19, v147
	v_mul_f32_e32 v23, v23, v147
	v_mul_f32_e32 v27, v27, v147
	v_mul_f32_e32 v31, v31, v147
	v_mul_f32_e32 v35, v35, v147
	v_mul_f32_e32 v39, v39, v147
	v_mul_f32_e32 v43, v43, v147
	v_mul_f32_e32 v47, v47, v147
	v_mul_f32_e32 v51, v51, v147
	v_mul_f32_e32 v55, v55, v147
	v_mul_f32_e32 v59, v59, v147
	v_mul_f32_e32 v63, v63, v147
	v_mov_b32_dpp v162, v3 quad_perm:[1,0,3,2] row_mask:0xf bank_mask:0xf
	v_mov_b32_dpp v163, v7 quad_perm:[1,0,3,2] row_mask:0xf bank_mask:0xf
	v_mov_b32_dpp v164, v11 quad_perm:[1,0,3,2] row_mask:0xf bank_mask:0xf
	v_mov_b32_dpp v165, v15 quad_perm:[1,0,3,2] row_mask:0xf bank_mask:0xf
	v_mov_b32_dpp v166, v19 quad_perm:[1,0,3,2] row_mask:0xf bank_mask:0xf
	v_mov_b32_dpp v167, v23 quad_perm:[1,0,3,2] row_mask:0xf bank_mask:0xf
	v_mov_b32_dpp v168, v27 quad_perm:[1,0,3,2] row_mask:0xf bank_mask:0xf
	v_mov_b32_dpp v169, v31 quad_perm:[1,0,3,2] row_mask:0xf bank_mask:0xf
	v_mov_b32_dpp v170, v35 quad_perm:[1,0,3,2] row_mask:0xf bank_mask:0xf
	v_mov_b32_dpp v171, v39 quad_perm:[1,0,3,2] row_mask:0xf bank_mask:0xf
	v_mov_b32_dpp v172, v43 quad_perm:[1,0,3,2] row_mask:0xf bank_mask:0xf
	v_mov_b32_dpp v173, v47 quad_perm:[1,0,3,2] row_mask:0xf bank_mask:0xf
	v_mov_b32_dpp v174, v51 quad_perm:[1,0,3,2] row_mask:0xf bank_mask:0xf
	v_mov_b32_dpp v175, v55 quad_perm:[1,0,3,2] row_mask:0xf bank_mask:0xf
	v_mov_b32_dpp v176, v59 quad_perm:[1,0,3,2] row_mask:0xf bank_mask:0xf
	v_mov_b32_dpp v177, v63 quad_perm:[1,0,3,2] row_mask:0xf bank_mask:0xf
	v_cvt_pk_bf16_f32 v3, v3, v162
	v_cvt_pk_bf16_f32 v7, v7, v163
	v_cvt_pk_bf16_f32 v11, v11, v164
	v_cvt_pk_bf16_f32 v15, v15, v165
	v_cvt_pk_bf16_f32 v19, v19, v166
	v_cvt_pk_bf16_f32 v23, v23, v167
	v_cvt_pk_bf16_f32 v27, v27, v168
	v_cvt_pk_bf16_f32 v31, v31, v169
	v_cvt_pk_bf16_f32 v35, v35, v170
	v_cvt_pk_bf16_f32 v39, v39, v171
	v_cvt_pk_bf16_f32 v43, v43, v172
	v_cvt_pk_bf16_f32 v47, v47, v173
	v_cvt_pk_bf16_f32 v51, v51, v174
	v_cvt_pk_bf16_f32 v55, v55, v175
	v_cvt_pk_bf16_f32 v59, v59, v176
	v_cvt_pk_bf16_f32 v63, v63, v177
	s_mov_b64 exec, s[76:77]
	global_store_dword v205, v3, s[36:37] offset:0
	global_store_dword v205, v7, s[36:37] offset:32
	global_store_dword v205, v11, s[36:37] offset:64
	global_store_dword v205, v15, s[36:37] offset:96
	global_store_dword v205, v19, s[36:37] offset:128
	global_store_dword v205, v23, s[36:37] offset:160
	global_store_dword v205, v27, s[36:37] offset:192
	global_store_dword v205, v31, s[36:37] offset:224
	global_store_dword v205, v35, s[36:37] offset:256
	global_store_dword v205, v39, s[36:37] offset:288
	global_store_dword v205, v43, s[36:37] offset:320
	global_store_dword v205, v47, s[36:37] offset:352
	global_store_dword v205, v51, s[36:37] offset:384
	global_store_dword v205, v55, s[36:37] offset:416
	global_store_dword v205, v59, s[36:37] offset:448
	global_store_dword v205, v63, s[36:37] offset:480
	s_mov_b64 exec, -1
	v_add_u32_e32 v205, 0x2000, v204
	v_mul_f32_e32 v4, v4, v148
	v_mul_f32_e32 v8, v8, v148
	v_mul_f32_e32 v12, v12, v148
	v_mul_f32_e32 v16, v16, v148
	v_mul_f32_e32 v20, v20, v148
	v_mul_f32_e32 v24, v24, v148
	v_mul_f32_e32 v28, v28, v148
	v_mul_f32_e32 v32, v32, v148
	v_mul_f32_e32 v36, v36, v148
	v_mul_f32_e32 v40, v40, v148
	v_mul_f32_e32 v44, v44, v148
	v_mul_f32_e32 v48, v48, v148
	v_mul_f32_e32 v52, v52, v148
	v_mul_f32_e32 v56, v56, v148
	v_mul_f32_e32 v60, v60, v148
	v_mul_f32_e32 v64, v64, v148
	v_mov_b32_dpp v162, v4 quad_perm:[1,0,3,2] row_mask:0xf bank_mask:0xf
	v_mov_b32_dpp v163, v8 quad_perm:[1,0,3,2] row_mask:0xf bank_mask:0xf
	v_mov_b32_dpp v164, v12 quad_perm:[1,0,3,2] row_mask:0xf bank_mask:0xf
	v_mov_b32_dpp v165, v16 quad_perm:[1,0,3,2] row_mask:0xf bank_mask:0xf
	v_mov_b32_dpp v166, v20 quad_perm:[1,0,3,2] row_mask:0xf bank_mask:0xf
	v_mov_b32_dpp v167, v24 quad_perm:[1,0,3,2] row_mask:0xf bank_mask:0xf
	v_mov_b32_dpp v168, v28 quad_perm:[1,0,3,2] row_mask:0xf bank_mask:0xf
	v_mov_b32_dpp v169, v32 quad_perm:[1,0,3,2] row_mask:0xf bank_mask:0xf
	v_mov_b32_dpp v170, v36 quad_perm:[1,0,3,2] row_mask:0xf bank_mask:0xf
	v_mov_b32_dpp v171, v40 quad_perm:[1,0,3,2] row_mask:0xf bank_mask:0xf
	v_mov_b32_dpp v172, v44 quad_perm:[1,0,3,2] row_mask:0xf bank_mask:0xf
	v_mov_b32_dpp v173, v48 quad_perm:[1,0,3,2] row_mask:0xf bank_mask:0xf
	v_mov_b32_dpp v174, v52 quad_perm:[1,0,3,2] row_mask:0xf bank_mask:0xf
	v_mov_b32_dpp v175, v56 quad_perm:[1,0,3,2] row_mask:0xf bank_mask:0xf
	v_mov_b32_dpp v176, v60 quad_perm:[1,0,3,2] row_mask:0xf bank_mask:0xf
	v_mov_b32_dpp v177, v64 quad_perm:[1,0,3,2] row_mask:0xf bank_mask:0xf
	v_cvt_pk_bf16_f32 v4, v4, v162
	v_cvt_pk_bf16_f32 v8, v8, v163
	v_cvt_pk_bf16_f32 v12, v12, v164
	v_cvt_pk_bf16_f32 v16, v16, v165
	v_cvt_pk_bf16_f32 v20, v20, v166
	v_cvt_pk_bf16_f32 v24, v24, v167
	v_cvt_pk_bf16_f32 v28, v28, v168
	v_cvt_pk_bf16_f32 v32, v32, v169
	v_cvt_pk_bf16_f32 v36, v36, v170
	v_cvt_pk_bf16_f32 v40, v40, v171
	v_cvt_pk_bf16_f32 v44, v44, v172
	v_cvt_pk_bf16_f32 v48, v48, v173
	v_cvt_pk_bf16_f32 v52, v52, v174
	v_cvt_pk_bf16_f32 v56, v56, v175
	v_cvt_pk_bf16_f32 v60, v60, v176
	v_cvt_pk_bf16_f32 v64, v64, v177
	s_mov_b64 exec, s[76:77]
	global_store_dword v205, v4, s[36:37] offset:0
	global_store_dword v205, v8, s[36:37] offset:32
	global_store_dword v205, v12, s[36:37] offset:64
	global_store_dword v205, v16, s[36:37] offset:96
	global_store_dword v205, v20, s[36:37] offset:128
	global_store_dword v205, v24, s[36:37] offset:160
	global_store_dword v205, v28, s[36:37] offset:192
	global_store_dword v205, v32, s[36:37] offset:224
	global_store_dword v205, v36, s[36:37] offset:256
	global_store_dword v205, v40, s[36:37] offset:288
	global_store_dword v205, v44, s[36:37] offset:320
	global_store_dword v205, v48, s[36:37] offset:352
	global_store_dword v205, v52, s[36:37] offset:384
	global_store_dword v205, v56, s[36:37] offset:416
	global_store_dword v205, v60, s[36:37] offset:448
	global_store_dword v205, v64, s[36:37] offset:480
	s_mov_b64 exec, -1
	v_add_u32_e32 v205, 0x3000, v204
	v_mul_f32_e32 v5, v5, v149
	v_mul_f32_e32 v9, v9, v149
	v_mul_f32_e32 v13, v13, v149
	v_mul_f32_e32 v17, v17, v149
	v_mul_f32_e32 v21, v21, v149
	v_mul_f32_e32 v25, v25, v149
	v_mul_f32_e32 v29, v29, v149
	v_mul_f32_e32 v33, v33, v149
	v_mul_f32_e32 v37, v37, v149
	v_mul_f32_e32 v41, v41, v149
	v_mul_f32_e32 v45, v45, v149
	v_mul_f32_e32 v49, v49, v149
	v_mul_f32_e32 v53, v53, v149
	v_mul_f32_e32 v57, v57, v149
	v_mul_f32_e32 v61, v61, v149
	v_mul_f32_e32 v65, v65, v149
	v_mov_b32_dpp v162, v5 quad_perm:[1,0,3,2] row_mask:0xf bank_mask:0xf
	v_mov_b32_dpp v163, v9 quad_perm:[1,0,3,2] row_mask:0xf bank_mask:0xf
	v_mov_b32_dpp v164, v13 quad_perm:[1,0,3,2] row_mask:0xf bank_mask:0xf
	v_mov_b32_dpp v165, v17 quad_perm:[1,0,3,2] row_mask:0xf bank_mask:0xf
	v_mov_b32_dpp v166, v21 quad_perm:[1,0,3,2] row_mask:0xf bank_mask:0xf
	v_mov_b32_dpp v167, v25 quad_perm:[1,0,3,2] row_mask:0xf bank_mask:0xf
	v_mov_b32_dpp v168, v29 quad_perm:[1,0,3,2] row_mask:0xf bank_mask:0xf
	v_mov_b32_dpp v169, v33 quad_perm:[1,0,3,2] row_mask:0xf bank_mask:0xf
	v_mov_b32_dpp v170, v37 quad_perm:[1,0,3,2] row_mask:0xf bank_mask:0xf
	v_mov_b32_dpp v171, v41 quad_perm:[1,0,3,2] row_mask:0xf bank_mask:0xf
	v_mov_b32_dpp v172, v45 quad_perm:[1,0,3,2] row_mask:0xf bank_mask:0xf
	v_mov_b32_dpp v173, v49 quad_perm:[1,0,3,2] row_mask:0xf bank_mask:0xf
	v_mov_b32_dpp v174, v53 quad_perm:[1,0,3,2] row_mask:0xf bank_mask:0xf
	v_mov_b32_dpp v175, v57 quad_perm:[1,0,3,2] row_mask:0xf bank_mask:0xf
	v_mov_b32_dpp v176, v61 quad_perm:[1,0,3,2] row_mask:0xf bank_mask:0xf
	v_mov_b32_dpp v177, v65 quad_perm:[1,0,3,2] row_mask:0xf bank_mask:0xf
	v_cvt_pk_bf16_f32 v5, v5, v162
	v_cvt_pk_bf16_f32 v9, v9, v163
	v_cvt_pk_bf16_f32 v13, v13, v164
	v_cvt_pk_bf16_f32 v17, v17, v165
	v_cvt_pk_bf16_f32 v21, v21, v166
	v_cvt_pk_bf16_f32 v25, v25, v167
	v_cvt_pk_bf16_f32 v29, v29, v168
	v_cvt_pk_bf16_f32 v33, v33, v169
	v_cvt_pk_bf16_f32 v37, v37, v170
	v_cvt_pk_bf16_f32 v41, v41, v171
	v_cvt_pk_bf16_f32 v45, v45, v172
	v_cvt_pk_bf16_f32 v49, v49, v173
	v_cvt_pk_bf16_f32 v53, v53, v174
	v_cvt_pk_bf16_f32 v57, v57, v175
	v_cvt_pk_bf16_f32 v61, v61, v176
	v_cvt_pk_bf16_f32 v65, v65, v177
	s_mov_b64 exec, s[76:77]
	global_store_dword v205, v5, s[36:37] offset:0
	global_store_dword v205, v9, s[36:37] offset:32
	global_store_dword v205, v13, s[36:37] offset:64
	global_store_dword v205, v17, s[36:37] offset:96
	global_store_dword v205, v21, s[36:37] offset:128
	global_store_dword v205, v25, s[36:37] offset:160
	global_store_dword v205, v29, s[36:37] offset:192
	global_store_dword v205, v33, s[36:37] offset:224
	global_store_dword v205, v37, s[36:37] offset:256
	global_store_dword v205, v41, s[36:37] offset:288
	global_store_dword v205, v45, s[36:37] offset:320
	global_store_dword v205, v49, s[36:37] offset:352
	global_store_dword v205, v53, s[36:37] offset:384
	global_store_dword v205, v57, s[36:37] offset:416
	global_store_dword v205, v61, s[36:37] offset:448
	global_store_dword v205, v65, s[36:37] offset:480
	s_mov_b64 exec, -1
	v_add_u32_e32 v205, 0x10000, v204
	v_mul_f32_e32 v66, v66, v150
	v_mul_f32_e32 v70, v70, v150
	v_mul_f32_e32 v74, v74, v150
	v_mul_f32_e32 v78, v78, v150
	v_mul_f32_e32 v82, v82, v150
	v_mul_f32_e32 v86, v86, v150
	v_mul_f32_e32 v90, v90, v150
	v_mul_f32_e32 v94, v94, v150
	v_mul_f32_e32 v98, v98, v150
	v_mul_f32_e32 v102, v102, v150
	v_mul_f32_e32 v106, v106, v150
	v_mul_f32_e32 v110, v110, v150
	v_mul_f32_e32 v114, v114, v150
	v_mul_f32_e32 v118, v118, v150
	v_mul_f32_e32 v122, v122, v150
	v_mul_f32_e32 v126, v126, v150
	v_mov_b32_dpp v162, v66 quad_perm:[1,0,3,2] row_mask:0xf bank_mask:0xf
	v_mov_b32_dpp v163, v70 quad_perm:[1,0,3,2] row_mask:0xf bank_mask:0xf
	v_mov_b32_dpp v164, v74 quad_perm:[1,0,3,2] row_mask:0xf bank_mask:0xf
	v_mov_b32_dpp v165, v78 quad_perm:[1,0,3,2] row_mask:0xf bank_mask:0xf
	v_mov_b32_dpp v166, v82 quad_perm:[1,0,3,2] row_mask:0xf bank_mask:0xf
	v_mov_b32_dpp v167, v86 quad_perm:[1,0,3,2] row_mask:0xf bank_mask:0xf
	v_mov_b32_dpp v168, v90 quad_perm:[1,0,3,2] row_mask:0xf bank_mask:0xf
	v_mov_b32_dpp v169, v94 quad_perm:[1,0,3,2] row_mask:0xf bank_mask:0xf
	v_mov_b32_dpp v170, v98 quad_perm:[1,0,3,2] row_mask:0xf bank_mask:0xf
	v_mov_b32_dpp v171, v102 quad_perm:[1,0,3,2] row_mask:0xf bank_mask:0xf
	v_mov_b32_dpp v172, v106 quad_perm:[1,0,3,2] row_mask:0xf bank_mask:0xf
	v_mov_b32_dpp v173, v110 quad_perm:[1,0,3,2] row_mask:0xf bank_mask:0xf
	v_mov_b32_dpp v174, v114 quad_perm:[1,0,3,2] row_mask:0xf bank_mask:0xf
	v_mov_b32_dpp v175, v118 quad_perm:[1,0,3,2] row_mask:0xf bank_mask:0xf
	v_mov_b32_dpp v176, v122 quad_perm:[1,0,3,2] row_mask:0xf bank_mask:0xf
	v_mov_b32_dpp v177, v126 quad_perm:[1,0,3,2] row_mask:0xf bank_mask:0xf
	v_cvt_pk_bf16_f32 v66, v66, v162
	v_cvt_pk_bf16_f32 v70, v70, v163
	v_cvt_pk_bf16_f32 v74, v74, v164
	v_cvt_pk_bf16_f32 v78, v78, v165
	v_cvt_pk_bf16_f32 v82, v82, v166
	v_cvt_pk_bf16_f32 v86, v86, v167
	v_cvt_pk_bf16_f32 v90, v90, v168
	v_cvt_pk_bf16_f32 v94, v94, v169
	v_cvt_pk_bf16_f32 v98, v98, v170
	v_cvt_pk_bf16_f32 v102, v102, v171
	v_cvt_pk_bf16_f32 v106, v106, v172
	v_cvt_pk_bf16_f32 v110, v110, v173
	v_cvt_pk_bf16_f32 v114, v114, v174
	v_cvt_pk_bf16_f32 v118, v118, v175
	v_cvt_pk_bf16_f32 v122, v122, v176
	v_cvt_pk_bf16_f32 v126, v126, v177
	s_mov_b64 exec, s[76:77]
	global_store_dword v205, v66, s[36:37] offset:0
	global_store_dword v205, v70, s[36:37] offset:32
	global_store_dword v205, v74, s[36:37] offset:64
	global_store_dword v205, v78, s[36:37] offset:96
	global_store_dword v205, v82, s[36:37] offset:128
	global_store_dword v205, v86, s[36:37] offset:160
	global_store_dword v205, v90, s[36:37] offset:192
	global_store_dword v205, v94, s[36:37] offset:224
	global_store_dword v205, v98, s[36:37] offset:256
	global_store_dword v205, v102, s[36:37] offset:288
	global_store_dword v205, v106, s[36:37] offset:320
	global_store_dword v205, v110, s[36:37] offset:352
	global_store_dword v205, v114, s[36:37] offset:384
	global_store_dword v205, v118, s[36:37] offset:416
	global_store_dword v205, v122, s[36:37] offset:448
	global_store_dword v205, v126, s[36:37] offset:480
	s_mov_b64 exec, -1
	v_add_u32_e32 v205, 0x11000, v204
	v_mul_f32_e32 v67, v67, v151
	v_mul_f32_e32 v71, v71, v151
	v_mul_f32_e32 v75, v75, v151
	v_mul_f32_e32 v79, v79, v151
	v_mul_f32_e32 v83, v83, v151
	v_mul_f32_e32 v87, v87, v151
	v_mul_f32_e32 v91, v91, v151
	v_mul_f32_e32 v95, v95, v151
	v_mul_f32_e32 v99, v99, v151
	v_mul_f32_e32 v103, v103, v151
	v_mul_f32_e32 v107, v107, v151
	v_mul_f32_e32 v111, v111, v151
	v_mul_f32_e32 v115, v115, v151
	v_mul_f32_e32 v119, v119, v151
	v_mul_f32_e32 v123, v123, v151
	v_mul_f32_e32 v127, v127, v151
	v_mov_b32_dpp v162, v67 quad_perm:[1,0,3,2] row_mask:0xf bank_mask:0xf
	v_mov_b32_dpp v163, v71 quad_perm:[1,0,3,2] row_mask:0xf bank_mask:0xf
	v_mov_b32_dpp v164, v75 quad_perm:[1,0,3,2] row_mask:0xf bank_mask:0xf
	v_mov_b32_dpp v165, v79 quad_perm:[1,0,3,2] row_mask:0xf bank_mask:0xf
	v_mov_b32_dpp v166, v83 quad_perm:[1,0,3,2] row_mask:0xf bank_mask:0xf
	v_mov_b32_dpp v167, v87 quad_perm:[1,0,3,2] row_mask:0xf bank_mask:0xf
	v_mov_b32_dpp v168, v91 quad_perm:[1,0,3,2] row_mask:0xf bank_mask:0xf
	v_mov_b32_dpp v169, v95 quad_perm:[1,0,3,2] row_mask:0xf bank_mask:0xf
	v_mov_b32_dpp v170, v99 quad_perm:[1,0,3,2] row_mask:0xf bank_mask:0xf
	v_mov_b32_dpp v171, v103 quad_perm:[1,0,3,2] row_mask:0xf bank_mask:0xf
	v_mov_b32_dpp v172, v107 quad_perm:[1,0,3,2] row_mask:0xf bank_mask:0xf
	v_mov_b32_dpp v173, v111 quad_perm:[1,0,3,2] row_mask:0xf bank_mask:0xf
	v_mov_b32_dpp v174, v115 quad_perm:[1,0,3,2] row_mask:0xf bank_mask:0xf
	v_mov_b32_dpp v175, v119 quad_perm:[1,0,3,2] row_mask:0xf bank_mask:0xf
	v_mov_b32_dpp v176, v123 quad_perm:[1,0,3,2] row_mask:0xf bank_mask:0xf
	v_mov_b32_dpp v177, v127 quad_perm:[1,0,3,2] row_mask:0xf bank_mask:0xf
	v_cvt_pk_bf16_f32 v67, v67, v162
	v_cvt_pk_bf16_f32 v71, v71, v163
	v_cvt_pk_bf16_f32 v75, v75, v164
	v_cvt_pk_bf16_f32 v79, v79, v165
	v_cvt_pk_bf16_f32 v83, v83, v166
	v_cvt_pk_bf16_f32 v87, v87, v167
	v_cvt_pk_bf16_f32 v91, v91, v168
	v_cvt_pk_bf16_f32 v95, v95, v169
	v_cvt_pk_bf16_f32 v99, v99, v170
	v_cvt_pk_bf16_f32 v103, v103, v171
	v_cvt_pk_bf16_f32 v107, v107, v172
	v_cvt_pk_bf16_f32 v111, v111, v173
	v_cvt_pk_bf16_f32 v115, v115, v174
	v_cvt_pk_bf16_f32 v119, v119, v175
	v_cvt_pk_bf16_f32 v123, v123, v176
	v_cvt_pk_bf16_f32 v127, v127, v177
	s_mov_b64 exec, s[76:77]
	global_store_dword v205, v67, s[36:37] offset:0
	global_store_dword v205, v71, s[36:37] offset:32
	global_store_dword v205, v75, s[36:37] offset:64
	global_store_dword v205, v79, s[36:37] offset:96
	global_store_dword v205, v83, s[36:37] offset:128
	global_store_dword v205, v87, s[36:37] offset:160
	global_store_dword v205, v91, s[36:37] offset:192
	global_store_dword v205, v95, s[36:37] offset:224
	global_store_dword v205, v99, s[36:37] offset:256
	global_store_dword v205, v103, s[36:37] offset:288
	global_store_dword v205, v107, s[36:37] offset:320
	global_store_dword v205, v111, s[36:37] offset:352
	global_store_dword v205, v115, s[36:37] offset:384
	global_store_dword v205, v119, s[36:37] offset:416
	global_store_dword v205, v123, s[36:37] offset:448
	global_store_dword v205, v127, s[36:37] offset:480
	s_mov_b64 exec, -1
	v_add_u32_e32 v205, 0x12000, v204
	v_mul_f32_e32 v68, v68, v152
	v_mul_f32_e32 v72, v72, v152
	v_mul_f32_e32 v76, v76, v152
	v_mul_f32_e32 v80, v80, v152
	v_mul_f32_e32 v84, v84, v152
	v_mul_f32_e32 v88, v88, v152
	v_mul_f32_e32 v92, v92, v152
	v_mul_f32_e32 v96, v96, v152
	v_mul_f32_e32 v100, v100, v152
	v_mul_f32_e32 v104, v104, v152
	v_mul_f32_e32 v108, v108, v152
	v_mul_f32_e32 v112, v112, v152
	v_mul_f32_e32 v116, v116, v152
	v_mul_f32_e32 v120, v120, v152
	v_mul_f32_e32 v124, v124, v152
	v_mul_f32_e32 v128, v128, v152
	v_mov_b32_dpp v162, v68 quad_perm:[1,0,3,2] row_mask:0xf bank_mask:0xf
	v_mov_b32_dpp v163, v72 quad_perm:[1,0,3,2] row_mask:0xf bank_mask:0xf
	v_mov_b32_dpp v164, v76 quad_perm:[1,0,3,2] row_mask:0xf bank_mask:0xf
	v_mov_b32_dpp v165, v80 quad_perm:[1,0,3,2] row_mask:0xf bank_mask:0xf
	v_mov_b32_dpp v166, v84 quad_perm:[1,0,3,2] row_mask:0xf bank_mask:0xf
	v_mov_b32_dpp v167, v88 quad_perm:[1,0,3,2] row_mask:0xf bank_mask:0xf
	v_mov_b32_dpp v168, v92 quad_perm:[1,0,3,2] row_mask:0xf bank_mask:0xf
	v_mov_b32_dpp v169, v96 quad_perm:[1,0,3,2] row_mask:0xf bank_mask:0xf
	v_mov_b32_dpp v170, v100 quad_perm:[1,0,3,2] row_mask:0xf bank_mask:0xf
	v_mov_b32_dpp v171, v104 quad_perm:[1,0,3,2] row_mask:0xf bank_mask:0xf
	v_mov_b32_dpp v172, v108 quad_perm:[1,0,3,2] row_mask:0xf bank_mask:0xf
	v_mov_b32_dpp v173, v112 quad_perm:[1,0,3,2] row_mask:0xf bank_mask:0xf
	v_mov_b32_dpp v174, v116 quad_perm:[1,0,3,2] row_mask:0xf bank_mask:0xf
	v_mov_b32_dpp v175, v120 quad_perm:[1,0,3,2] row_mask:0xf bank_mask:0xf
	v_mov_b32_dpp v176, v124 quad_perm:[1,0,3,2] row_mask:0xf bank_mask:0xf
	v_mov_b32_dpp v177, v128 quad_perm:[1,0,3,2] row_mask:0xf bank_mask:0xf
	v_cvt_pk_bf16_f32 v68, v68, v162
	v_cvt_pk_bf16_f32 v72, v72, v163
	v_cvt_pk_bf16_f32 v76, v76, v164
	v_cvt_pk_bf16_f32 v80, v80, v165
	v_cvt_pk_bf16_f32 v84, v84, v166
	v_cvt_pk_bf16_f32 v88, v88, v167
	v_cvt_pk_bf16_f32 v92, v92, v168
	v_cvt_pk_bf16_f32 v96, v96, v169
	v_cvt_pk_bf16_f32 v100, v100, v170
	v_cvt_pk_bf16_f32 v104, v104, v171
	v_cvt_pk_bf16_f32 v108, v108, v172
	v_cvt_pk_bf16_f32 v112, v112, v173
	v_cvt_pk_bf16_f32 v116, v116, v174
	v_cvt_pk_bf16_f32 v120, v120, v175
	v_cvt_pk_bf16_f32 v124, v124, v176
	v_cvt_pk_bf16_f32 v128, v128, v177
	s_mov_b64 exec, s[76:77]
	global_store_dword v205, v68, s[36:37] offset:0
	global_store_dword v205, v72, s[36:37] offset:32
	global_store_dword v205, v76, s[36:37] offset:64
	global_store_dword v205, v80, s[36:37] offset:96
	global_store_dword v205, v84, s[36:37] offset:128
	global_store_dword v205, v88, s[36:37] offset:160
	global_store_dword v205, v92, s[36:37] offset:192
	global_store_dword v205, v96, s[36:37] offset:224
	global_store_dword v205, v100, s[36:37] offset:256
	global_store_dword v205, v104, s[36:37] offset:288
	global_store_dword v205, v108, s[36:37] offset:320
	global_store_dword v205, v112, s[36:37] offset:352
	global_store_dword v205, v116, s[36:37] offset:384
	global_store_dword v205, v120, s[36:37] offset:416
	global_store_dword v205, v124, s[36:37] offset:448
	global_store_dword v205, v128, s[36:37] offset:480
	s_mov_b64 exec, -1
	v_add_u32_e32 v205, 0x13000, v204
	v_mul_f32_e32 v69, v69, v153
	v_mul_f32_e32 v73, v73, v153
	v_mul_f32_e32 v77, v77, v153
	v_mul_f32_e32 v81, v81, v153
	v_mul_f32_e32 v85, v85, v153
	v_mul_f32_e32 v89, v89, v153
	v_mul_f32_e32 v93, v93, v153
	v_mul_f32_e32 v97, v97, v153
	v_mul_f32_e32 v101, v101, v153
	v_mul_f32_e32 v105, v105, v153
	v_mul_f32_e32 v109, v109, v153
	v_mul_f32_e32 v113, v113, v153
	v_mul_f32_e32 v117, v117, v153
	v_mul_f32_e32 v121, v121, v153
	v_mul_f32_e32 v125, v125, v153
	v_mul_f32_e32 v129, v129, v153
	v_mov_b32_dpp v162, v69 quad_perm:[1,0,3,2] row_mask:0xf bank_mask:0xf
	v_mov_b32_dpp v163, v73 quad_perm:[1,0,3,2] row_mask:0xf bank_mask:0xf
	v_mov_b32_dpp v164, v77 quad_perm:[1,0,3,2] row_mask:0xf bank_mask:0xf
	v_mov_b32_dpp v165, v81 quad_perm:[1,0,3,2] row_mask:0xf bank_mask:0xf
	v_mov_b32_dpp v166, v85 quad_perm:[1,0,3,2] row_mask:0xf bank_mask:0xf
	v_mov_b32_dpp v167, v89 quad_perm:[1,0,3,2] row_mask:0xf bank_mask:0xf
	v_mov_b32_dpp v168, v93 quad_perm:[1,0,3,2] row_mask:0xf bank_mask:0xf
	v_mov_b32_dpp v169, v97 quad_perm:[1,0,3,2] row_mask:0xf bank_mask:0xf
	v_mov_b32_dpp v170, v101 quad_perm:[1,0,3,2] row_mask:0xf bank_mask:0xf
	v_mov_b32_dpp v171, v105 quad_perm:[1,0,3,2] row_mask:0xf bank_mask:0xf
	v_mov_b32_dpp v172, v109 quad_perm:[1,0,3,2] row_mask:0xf bank_mask:0xf
	v_mov_b32_dpp v173, v113 quad_perm:[1,0,3,2] row_mask:0xf bank_mask:0xf
	v_mov_b32_dpp v174, v117 quad_perm:[1,0,3,2] row_mask:0xf bank_mask:0xf
	v_mov_b32_dpp v175, v121 quad_perm:[1,0,3,2] row_mask:0xf bank_mask:0xf
	v_mov_b32_dpp v176, v125 quad_perm:[1,0,3,2] row_mask:0xf bank_mask:0xf
	v_mov_b32_dpp v177, v129 quad_perm:[1,0,3,2] row_mask:0xf bank_mask:0xf
	v_cvt_pk_bf16_f32 v69, v69, v162
	v_cvt_pk_bf16_f32 v73, v73, v163
	v_cvt_pk_bf16_f32 v77, v77, v164
	v_cvt_pk_bf16_f32 v81, v81, v165
	v_cvt_pk_bf16_f32 v85, v85, v166
	v_cvt_pk_bf16_f32 v89, v89, v167
	v_cvt_pk_bf16_f32 v93, v93, v168
	v_cvt_pk_bf16_f32 v97, v97, v169
	v_cvt_pk_bf16_f32 v101, v101, v170
	v_cvt_pk_bf16_f32 v105, v105, v171
	v_cvt_pk_bf16_f32 v109, v109, v172
	v_cvt_pk_bf16_f32 v113, v113, v173
	v_cvt_pk_bf16_f32 v117, v117, v174
	v_cvt_pk_bf16_f32 v121, v121, v175
	v_cvt_pk_bf16_f32 v125, v125, v176
	v_cvt_pk_bf16_f32 v129, v129, v177
	s_mov_b64 exec, s[76:77]
	global_store_dword v205, v69, s[36:37] offset:0
	global_store_dword v205, v73, s[36:37] offset:32
	global_store_dword v205, v77, s[36:37] offset:64
	global_store_dword v205, v81, s[36:37] offset:96
	global_store_dword v205, v85, s[36:37] offset:128
	global_store_dword v205, v89, s[36:37] offset:160
	global_store_dword v205, v93, s[36:37] offset:192
	global_store_dword v205, v97, s[36:37] offset:224
	global_store_dword v205, v101, s[36:37] offset:256
	global_store_dword v205, v105, s[36:37] offset:288
	global_store_dword v205, v109, s[36:37] offset:320
	global_store_dword v205, v113, s[36:37] offset:352
	global_store_dword v205, v117, s[36:37] offset:384
	global_store_dword v205, v121, s[36:37] offset:416
	global_store_dword v205, v125, s[36:37] offset:448
	global_store_dword v205, v129, s[36:37] offset:480
	s_mov_b64 exec, -1
	s_mov_b64 s[36:37], -1
	s_branch .LBB0_2404

	.amdhsa_kernel _Z9trunk_fwd4Args
		.amdhsa_group_segment_fixed_size 0
		.amdhsa_private_segment_fixed_size 0
		.amdhsa_kernarg_size 808
		.amdhsa_user_sgpr_count 2
		.amdhsa_user_sgpr_dispatch_ptr 0
		.amdhsa_user_sgpr_queue_ptr 0
		.amdhsa_user_sgpr_kernarg_segment_ptr 1
		.amdhsa_user_sgpr_dispatch_id 0
		.amdhsa_user_sgpr_kernarg_preload_length 0
		.amdhsa_user_sgpr_kernarg_preload_offset 0
		.amdhsa_user_sgpr_private_segment_size 0
		.amdhsa_uses_dynamic_stack 0
		.amdhsa_enable_private_segment 0
		.amdhsa_system_sgpr_workgroup_id_x 1
		.amdhsa_system_sgpr_workgroup_id_y 0
		.amdhsa_system_sgpr_workgroup_id_z 0
		.amdhsa_system_sgpr_workgroup_info 0
		.amdhsa_system_vgpr_workitem_id 0
		.amdhsa_next_free_vgpr 256
		.amdhsa_next_free_sgpr 98
		.amdhsa_accum_offset 256
		.amdhsa_reserve_vcc 1
		.amdhsa_float_round_mode_32 0
		.amdhsa_float_round_mode_16_64 0
		.amdhsa_float_denorm_mode_32 3
		.amdhsa_float_denorm_mode_16_64 3
		.amdhsa_dx10_clamp 1
		.amdhsa_ieee_mode 1
		.amdhsa_fp16_overflow 0
		.amdhsa_tg_split 0
		.amdhsa_exception_fp_ieee_invalid_op 0
		.amdhsa_exception_fp_denorm_src 0
		.amdhsa_exception_fp_ieee_div_zero 0
		.amdhsa_exception_fp_ieee_overflow 0
		.amdhsa_exception_fp_ieee_underflow 0
		.amdhsa_exception_fp_ieee_inexact 0
		.amdhsa_exception_int_div_zero 0
	.end_amdhsa_kernel

amdhsa.kernels:
  - .agpr_count:     0
    .args:
      - .offset:         0
        .size:           552
        .value_kind:     by_value
      - .offset:         552
        .size:           4
        .value_kind:     hidden_block_count_x
      - .offset:         556
        .size:           4
        .value_kind:     hidden_block_count_y
      - .offset:         560
        .size:           4
        .value_kind:     hidden_block_count_z
      - .offset:         564
        .size:           2
        .value_kind:     hidden_group_size_x
      - .offset:         566
        .size:           2
        .value_kind:     hidden_group_size_y
      - .offset:         568
        .size:           2
        .value_kind:     hidden_group_size_z
      - .offset:         570
        .size:           2
        .value_kind:     hidden_remainder_x
      - .offset:         572
        .size:           2
        .value_kind:     hidden_remainder_y
      - .offset:         574
        .size:           2
        .value_kind:     hidden_remainder_z
      - .offset:         592
        .size:           8
        .value_kind:     hidden_global_offset_x
      - .offset:         600
        .size:           8
        .value_kind:     hidden_global_offset_y
      - .offset:         608
        .size:           8
        .value_kind:     hidden_global_offset_z
      - .offset:         616
        .size:           2
        .value_kind:     hidden_grid_dims
      - .offset:         672
        .size:           4
        .value_kind:     hidden_dynamic_lds_size
    .group_segment_fixed_size: 0
    .kernarg_segment_align: 8
    .kernarg_segment_size: 808
    .language:       OpenCL C
    .language_version:
      - 2
      - 0
    .max_flat_workgroup_size: 512
    .name:           _Z9trunk_fwd4Args
    .private_segment_fixed_size: 0
    .sgpr_count:     104
    .sgpr_spill_count: 113
    .symbol:         _Z9trunk_fwd4Args.kd
    .uniform_work_group_size: 1
    .uses_dynamic_stack: false
    .vgpr_count:     256
    .vgpr_spill_count: 0
    .wavefront_size: 64
